# v17: GEMM DMA drains removed, G1 restructured (next-tile prefetch before epilogue stores, hand epilogue), G3 hand epilogue, seq XCD-local item order, S5-Y tile order, setup item order
# speedup vs baseline: 1.0156x; 1.0156x over previous
; #define VBID ((int)(blockIdx.x * 2 + (otid() >> 8)))
; DI void phase_setup(const Params& p, char* lds) {
;     ...
;   for (int k_ = 0; k_ * VGRID < (NITEM); ++k_) {
;     int it = k_ * VGRID + VBID; const bool active_ = it < (NITEM); if (!active_) it = (NITEM) - 1;
;     if (it < 384) {
.LBB0_21:
	v_mov_b32_e32 v0, v182
	v_readlane_b32 s0, v251, 7
	v_ashrrev_i32_e32 v0, 8, v0
	s_add_i32 s0, s2, s0
	v_add_u32_e32 v19, s0, v0
	v_add_u32_e32 v0, 0x9c0, v19
	v_add_u32_e32 v18, 0xffffff00, v19
	v_cmp_gt_u32_e32 vcc, 0x100, v19
	s_nop 1
	v_cndmask_b32_e32 v0, v18, v0, vcc
	v_mov_b32_e32 v18, 0x9bf
	v_cmp_gt_u32_e32 vcc, 0xac0, v19
	s_nop 1
	v_cndmask_b32_e32 v19, v18, v0, vcc
	s_movk_i32 s0, 0x17f
	v_min_i32_e32 v18, 0xabf, v19
	v_cmp_lt_i32_e32 vcc, s0, v19
	s_mov_b64 s[12:13], 0
	s_and_saveexec_b64 s[0:1], vcc
	s_xor_b64 s[64:65], exec, s[0:1]
	s_cbranch_execnz .LBB0_24
	s_andn2_saveexec_b64 s[14:15], s[64:65]
	s_cbranch_execnz .LBB0_72

; DI unsigned pack2(float a, float b) { const hwf32x2 v = {a, b}; const hwbf16x2 r = __builtin_convertvector(v, hwbf16x2); return __builtin_bit_cast(unsigned, r); }
; DI void tile8_order(int L, int nM, int nN, int& pm, int& pn) {
;   const int t = tile_remap(L, nM * nN), nig = 8 * nN, gid = t / nig, fm = gid * 8, gsz = (nM - fm) < 8 ? (nM - fm) : 8;
;   pm = fm + ((t % nig) % gsz); pn = (t % nig) / gsz;
; }
; DI void st_bf4(bf16_t* p, float a, float b, float c, float d) { uint2 v; v.x = pack2(a, b); v.y = pack2(c, d); *(uint2*)p = v; }
; DI void ld_bf4(const bf16_t* p, float& a, float& b, float& c, float& d) {
;   const uint2 v = *(const uint2*)p; a = __uint_as_float(v.x << 16); b = __uint_as_float(v.x & 0xffff0000u); c = __uint_as_float(v.y << 16); d = __uint_as_float(v.y & 0xffff0000u);
; }
; template <class FL, class FS>
; DI void gemm_dispatch(const Sub& s, char* lds_all, const bf16_t* A, const bf16_t* Bt, const int nN256, FL fl, FS fs) {
;   if (!s.samp) {
;     const int nM = 256;
;     for (int L = blockIdx.x; L < nM * nN256; L += gridDim.x) {
;       int pm, pn; tile8_order(L, nM, nN256, pm, pn);
;       gemm8_tile(lds_all, A, Bt, D, pm * 256, pn * 256, fl, fs);
.LBB0_195:
	s_or_b64 exec, exec, s[4:5]
	v_readlane_b32 s0, v251, 0
	s_cmpk_gt_i32 s0, 0x7ff
	s_mov_b32 s33, 0
	s_mov_b32 s0, 0
	s_waitcnt lgkmcnt(0)
	v_mov_b32_e32 v0, v182
	s_barrier
	s_cbranch_scc1 .LBB0_460
	v_readlane_b32 s2, v251, 0
	s_bitcmp1_b32 s2, 3
	s_cbranch_scc0 .Lg1_nodelay
	s_sleep 127
	s_sleep 127
	s_sleep 127
.Lg1_nodelay:
	s_ashr_i32 s1, s0, 31
	v_readlane_b32 s2, v251, 3
	v_readlane_b32 s3, v251, 4
	s_add_u32 s0, s2, s0
	s_addc_u32 s1, s3, s1
	s_load_dwordx2 s[12:13], s[0:1], 0xf8
	s_mov_b32 s42, 0x10000
	s_mov_b32 s43, 0x14000
	s_mov_b64 s[14:15], 0x80
	s_mov_b32 s46, 0x18000
	s_waitcnt lgkmcnt(0)
	s_add_u32 s44, s12, 0x1800000
	s_addc_u32 s45, s13, 0
	s_add_u32 s16, s12, 0x9880000
	s_addc_u32 s17, s13, 0
	s_add_u32 s18, s12, 0x11900000
	s_addc_u32 s19, s13, 0
	s_add_u32 s20, s12, 0x1514000
	s_addc_u32 s21, s13, 0
	s_mov_b32 s47, 0x1c000
	s_mov_b64 s[22:23], 0x1840080
	s_mov_b64 s[24:25], 0x100
	s_mov_b64 s[26:27], 0x1800100
	s_mov_b64 s[28:29], 0x40100
	s_mov_b64 s[30:31], 0x1840100
	s_mov_b64 s[34:35], 0x180
	s_mov_b64 s[36:37], 0x1800180
	s_mov_b64 s[38:39], 0x40180
	s_mov_b64 s[40:41], 0x780
	s_movk_i32 s48, 0x100
	s_mov_b32 s49, 0xffff
	v_mov_b32_e32 v129, 0
	s_movk_i32 s50, 0x3ff
	v_mov_b32_e32 v142, 1
	v_readlane_b32 s51, v251, 0
	s_waitcnt vmcnt(0)
	s_mov_b32 s98, 0
	s_branch .LBB0_199
.LBB0_199:
	s_lshl_b32 s0, s51, 8
	s_and_b32 s0, s0, 0x700
	s_ashr_i32 s1, s51, 3
	s_add_i32 s0, s0, s1
	v_mov_b32_e32 v128, v182
	s_ashr_i32 s1, s0, 31
	s_lshr_b32 s1, s1, 26
	v_ashrrev_i32_e32 v200, 31, v128
	v_lshrrev_b32_e32 v200, 26, v200
	s_add_i32 s1, s0, s1
	v_add_u32_e32 v200, v128, v200
	s_and_b32 s2, s1, 0xffc0
	v_ashrrev_i32_e32 v201, 6, v200
	v_bfe_i32 v200, v128, 27, 1
	s_sub_i32 s0, s0, s2
	v_lshlrev_b32_e32 v147, 4, v128
	v_lshrrev_b32_e32 v200, 22, v200
	s_bfe_i32 s2, s0, 0x80000
	v_add_u32_e32 v200, v147, v200
	s_bfe_u32 s2, s2, 0x3000c
	v_and_b32_e32 v200, 0xfffffc00, v200
	s_add_i32 s2, s0, s2
	v_sub_u32_e32 v200, v147, v200
	s_bfe_i32 s3, s2, 0x80000
	s_and_b32 s2, s2, 0xf8
	v_lshrrev_b32_e32 v202, 4, v200
	s_sub_i32 s0, s0, s2
	v_bitop3_b32 v202, v202, v200, 32 bitop3:0x6c
	v_ashrrev_i32_e32 v200, 31, v200
	s_sext_i32_i8 s0, s0
	s_lshl_b32 s1, s1, 5
	v_lshrrev_b32_e32 v200, 26, v200
	s_sext_i32_i16 s3, s3
	s_and_b32 s1, s1, 0xfffff800
	s_lshl_b32 s0, s0, 8
	v_lshlrev_b32_e32 v203, 3, v201
	v_add_u32_e32 v200, v202, v200
	s_add_i32 s6, s0, s1
	s_lshl_b32 s0, s3, 5
	v_and_b32_e32 v203, -16, v203
	v_ashrrev_i32_e32 v204, 6, v200
	s_and_b32 s4, s0, 0xffffff00
	v_add_u32_e32 v200, v204, v203
	v_mul_i32_i24_e32 v203, 64, v204
	s_ashr_i32 s5, s4, 31
	v_lshlrev_b32_e32 v201, 5, v201
	v_sub_u32_e32 v202, v202, v203
	s_lshl_b64 s[0:1], s[4:5], 11
	v_and_b32_e32 v201, 32, v201
	v_ashrrev_i16_sdwa v202, v142, sext(v202) dst_sel:DWORD dst_unused:UNUSED_PAD src0_sel:DWORD src1_sel:BYTE_0
	s_add_u32 s2, s12, s0
	v_add_u32_sdwa v202, v201, sext(v202) dst_sel:DWORD dst_unused:UNUSED_PAD src0_sel:DWORD src1_sel:WORD_0
	v_ashrrev_i32_e32 v201, 31, v200
	s_addc_u32 s3, s13, s1
	v_lshlrev_b64 v[200:201], 11, v[200:201]
	v_ashrrev_i32_e32 v203, 31, v202
	v_lshl_add_u64 v[204:205], s[2:3], 0, v[200:201]
	v_lshlrev_b64 v[202:203], 1, v[202:203]
	v_add_u32_e32 v153, 0x2000, v147
	v_lshl_add_u64 v[208:209], v[204:205], 0, v[202:203]
	v_ashrrev_i32_e32 v204, 31, v153
	v_lshrrev_b32_e32 v204, 22, v204
	v_add_u32_e32 v204, v153, v204
	v_ashrrev_i32_e32 v205, 10, v204
	v_mul_i32_i24_e32 v204, 0x400, v205
	v_sub_u32_e32 v204, v153, v204
	v_lshrrev_b32_e32 v206, 4, v204
	v_bitop3_b32 v206, v206, v204, 32 bitop3:0x6c
	v_ashrrev_i32_e32 v207, 31, v206
	v_lshrrev_b32_e32 v207, 26, v207
	v_add_u32_e32 v207, v206, v207
	v_lshlrev_b32_e32 v204, 3, v205
	v_ashrrev_i32_e32 v210, 6, v207
	v_and_b32_e32 v207, 0xc0, v207
	v_and_b32_e32 v204, -16, v204
	v_lshlrev_b32_e32 v205, 5, v205
	v_sub_u32_e32 v206, v206, v207
	v_add_u32_e32 v204, v210, v204
	v_and_b32_e32 v205, 32, v205
	v_ashrrev_i16_sdwa v206, v142, sext(v206) dst_sel:DWORD dst_unused:UNUSED_PAD src0_sel:DWORD src1_sel:BYTE_0
	v_add_u32_e32 v149, 0x10000, v147
	v_add_u32_sdwa v206, v205, sext(v206) dst_sel:DWORD dst_unused:UNUSED_PAD src0_sel:DWORD src1_sel:WORD_0
	v_ashrrev_i32_e32 v205, 31, v204
	v_readfirstlane_b32 s5, v149
	v_lshlrev_b64 v[204:205], 11, v[204:205]
	v_add_u32_e32 v155, 0x12000, v147
	s_mov_b32 m0, s5
	v_lshl_add_u64 v[210:211], s[2:3], 0, v[204:205]
	v_readfirstlane_b32 s2, v155
	s_ashr_i32 s7, s6, 31
	global_load_lds_dwordx4 v[208:209], off
	s_mov_b32 m0, s2
	s_lshl_b64 s[2:3], s[6:7], 11
	s_add_u32 s8, s44, s2
	s_addc_u32 s9, s45, s3
	v_lshl_add_u64 v[212:213], s[8:9], 0, v[200:201]
	v_lshl_add_u64 v[214:215], s[8:9], 0, v[204:205]
	s_or_b32 s8, s4, 0x80
	s_ashr_i32 s9, s8, 31
	s_lshl_b64 s[8:9], s[8:9], 11
	s_add_u32 s8, s12, s8
	v_ashrrev_i32_e32 v207, 31, v206
	s_addc_u32 s9, s13, s9
; #define STAGE(P, BASE, br, kt) do { const long _g = (long)(br) * K + (long)(kt) * 64; \
;     _Pragma("unroll") for (int _i = 0; _i < 2; ++_i) { const int _b = tidx * 16 + _i * 8192; int _r, _c; stage_rc8(_b, _r, _c); \
;       __builtin_amdgcn_global_load_lds((const unsigned*)(BASE + _g + (long)_r * K + _c), (LAS unsigned*)((LAS char*)(P) + _b), 16, 0, 0); } } while (0)
; #define LDA(dst, b, h) _Pragma("unroll") for (int m = 0; m < 4; ++m) _Pragma("unroll") for (int k = 0; k < 2; ++k) \
;     dst[m][k] = *reinterpret_cast<const bf16x8*>((const char*)SA(b, h) + lds_byte8(wr * 64 + m * 16 + fr, k * 32 + fq * 8))
; #define LDB(dst, b, h) _Pragma("unroll") for (int n = 0; n < 2; ++n) _Pragma("unroll") for (int k = 0; k < 2; ++k) \
;     dst[n][k] = *reinterpret_cast<const bf16x8*>((const char*)SB(b, h) + lds_byte8(wc * 32 + n * 16 + fr, k * 32 + fq * 8))
; #define WAIT_V(n) asm volatile("s_waitcnt vmcnt(" #n ")" ::: "memory")
; #define BAR __builtin_amdgcn_s_barrier()
; #define SCHED __builtin_amdgcn_sched_barrier(0)
; template <class FL, class FS>
; DI void gemm8_tile(char* shmc, const bf16_t* __restrict__ A, const bf16_t* __restrict__ Bt, const int K, const int brow, const int bcol, FL fl, FS fs) {
;     ...
;   STAGE(SB(0, 0), Bt, bcol, 0); STAGE(SA(0, 0), A, brow, 0);
;   STAGE(SB(0, 1), Bt, bcol + HALF, 0); STAGE(SA(0, 1), A, brow + HALF, 0);
;   if (wr == 1) BAR;
;   WAIT_V(4); BAR;
;   STAGE(SB(1, 0), Bt, bcol, 1); STAGE(SA(1, 0), A, brow, 1); STAGE(SB(1, 1), Bt, bcol + HALF, 1);
;   WAIT_V(6); BAR;
;   for (int t = 0; t < nt - 2; t += 2) {
;     LDB(B0, 0, 0); SCHED; LDA(At, 0, 0); STAGE(SA(1, 1), A, brow + HALF, t + 1);
	v_lshlrev_b64 v[206:207], 1, v[206:207]
	v_lshl_add_u64 v[216:217], s[8:9], 0, v[200:201]
	v_lshl_add_u64 v[218:219], s[8:9], 0, v[204:205]
	s_or_b32 s8, s6, 0x80
	v_lshl_add_u64 v[210:211], v[210:211], 0, v[206:207]
	v_readfirstlane_b32 s5, v147
	s_ashr_i32 s9, s8, 31
	global_load_lds_dwordx4 v[210:211], off
	v_lshl_add_u64 v[212:213], v[212:213], 0, v[202:203]
	s_mov_b32 m0, s5
	v_readfirstlane_b32 s5, v153
	v_add_u32_e32 v157, 0x14000, v147
	s_lshl_b64 s[8:9], s[8:9], 11
	global_load_lds_dwordx4 v[212:213], off
	v_lshl_add_u64 v[214:215], v[214:215], 0, v[206:207]
	s_mov_b32 m0, s5
	v_readfirstlane_b32 s5, v157
	v_add_u32_e32 v158, 0x16000, v147
	s_add_u32 s8, s44, s8
	global_load_lds_dwordx4 v[214:215], off
	v_lshl_add_u64 v[216:217], v[216:217], 0, v[202:203]
	s_mov_b32 m0, s5
	v_readfirstlane_b32 s5, v158
	s_addc_u32 s9, s45, s9
	v_add_u32_e32 v159, 0x4000, v147
	global_load_lds_dwordx4 v[216:217], off
	v_lshl_add_u64 v[218:219], v[218:219], 0, v[206:207]
	s_mov_b32 m0, s5
	v_lshl_add_u64 v[220:221], s[8:9], 0, v[200:201]
	v_readfirstlane_b32 s5, v159
	v_add_u32_e32 v160, 0x6000, v147
	global_load_lds_dwordx4 v[218:219], off
	v_lshl_add_u64 v[130:131], v[220:221], 0, v[202:203]
	s_mov_b32 m0, s5
	v_lshl_add_u64 v[220:221], s[8:9], 0, v[204:205]
	v_readfirstlane_b32 s5, v160
	global_load_lds_dwordx4 v[130:131], off
	v_lshl_add_u64 v[132:133], v[220:221], 0, v[206:207]
	s_mov_b32 m0, s5
	v_ashrrev_i32_e32 v220, 8, v128
	global_load_lds_dwordx4 v[132:133], off
	v_add_u32_e32 v161, 0x18000, v147
	v_add_u32_e32 v162, 0x1a000, v147
	v_readfirstlane_b32 s5, v161
	v_lshl_add_u64 v[208:209], v[208:209], 0, s[14:15]
	s_mov_b32 m0, s5
	v_readfirstlane_b32 s5, v162
	v_add_u32_e32 v163, 0x8000, v147
	global_load_lds_dwordx4 v[208:209], off
	v_lshl_add_u64 v[208:209], v[210:211], 0, s[14:15]
	s_mov_b32 m0, s5
	v_readfirstlane_b32 s5, v163
	v_add_u32_e32 v164, 0xa000, v147
	global_load_lds_dwordx4 v[208:209], off
	v_lshl_add_u64 v[208:209], v[212:213], 0, s[14:15]
	s_mov_b32 m0, s5
	v_readfirstlane_b32 s5, v164
	v_add_u32_e32 v165, 0x1c000, v147
	global_load_lds_dwordx4 v[208:209], off
	v_lshl_add_u64 v[208:209], v[214:215], 0, s[14:15]
	s_mov_b32 m0, s5
	v_readfirstlane_b32 s5, v165
	v_add_u32_e32 v167, 0x1e000, v147
	global_load_lds_dwordx4 v[208:209], off
	v_lshl_add_u64 v[208:209], v[216:217], 0, s[14:15]
	s_mov_b32 m0, s5
	v_readfirstlane_b32 s5, v167
	global_load_lds_dwordx4 v[208:209], off
	v_lshl_add_u64 v[208:209], v[218:219], 0, s[14:15]
	s_mov_b32 m0, s5
	v_and_b32_e32 v145, 15, v128
	global_load_lds_dwordx4 v[208:209], off
	v_bfe_u32 v144, v128, 4, 2
	v_lshlrev_b32_e32 v212, 2, v128
	v_lshlrev_b32_e32 v208, 4, v144
	v_lshlrev_b32_e32 v209, 6, v145
	v_and_b32_e32 v212, 32, v212
	v_or_b32_e32 v211, v208, v209
	v_bitop3_b32 v213, v208, v212, v209 bitop3:0x36
	v_lshlrev_b32_e32 v209, 6, v128
	v_and_b32_e32 v209, 0x3c0, v209
	v_bitop3_b32 v214, v211, s42, v212 bitop3:0xde
	v_bitop3_b32 v215, v211, s43, v212 bitop3:0xde
	v_bitop3_b32 v216, v211, s46, v212 bitop3:0xde
	v_bitop3_b32 v211, v211, s47, v212 bitop3:0xde
	v_bitop3_b32 v212, v209, v212, v208 bitop3:0x36
	v_lshl_add_u64 v[208:209], s[0:1], 0, v[200:201]
	v_lshl_add_u64 v[200:201], s[2:3], 0, v[200:201]
	v_bfe_u32 v143, v128, 6, 2
	v_lshlrev_b32_e32 v217, 13, v220
	v_lshl_add_u64 v[138:139], v[200:201], 0, v[202:203]
	v_lshl_add_u64 v[200:201], s[2:3], 0, v[204:205]
	v_lshlrev_b32_e32 v210, 12, v143
	v_lshlrev_b32_e32 v146, 6, v220
	v_or_b32_e32 v218, 0x800, v217
	v_or_b32_e32 v219, 0x1000, v217
	v_or_b32_e32 v220, 0x1800, v217
	v_lshl_add_u64 v[134:135], v[208:209], 0, v[202:203]
	v_lshl_add_u64 v[208:209], s[0:1], 0, v[204:205]
	v_lshl_add_u64 v[140:141], v[200:201], 0, v[206:207]
	v_lshl_add_u64 v[136:137], v[208:209], 0, v[206:207]
	v_add_u32_e32 v170, v214, v210
	v_add_u32_e32 v152, v213, v217
	v_add_u32_e32 v151, v212, v218
	v_add_u32_e32 v150, v212, v219
	v_add_u32_e32 v148, v212, v220
	v_add_u32_e32 v169, 0xc000, v147
	v_add_u32_e32 v168, 0xe000, v147
	v_add_u32_e32 v166, v215, v210
	v_add_u32_e32 v156, v216, v210
	v_add_u32_e32 v154, v211, v210
	v_lshl_add_u64 v[222:223], s[12:13], 0, v[138:139]
	v_readfirstlane_b32 s1, v169
	v_lshl_add_u64 v[222:223], v[222:223], 0, s[22:23]
	s_mov_b32 m0, s1
	v_lshl_add_u64 v[224:225], s[12:13], 0, v[140:141]
	v_readfirstlane_b32 s1, v168
	global_load_lds_dwordx4 v[222:223], off
	v_lshl_add_u64 v[224:225], v[224:225], 0, s[22:23]
	s_mov_b32 m0, s1
	s_nop 0
	global_load_lds_dwordx4 v[224:225], off
	s_cmp_eq_u32 s98, 0
	s_cbranch_scc1 .Lg1_first
	s_mov_b32 s101, 0
	s_branch .Lg1_epi
.Lg1_epi_ret0:
	v_lshrrev_b32_e32 v222, 8, v182
	v_cmp_eq_u32_e32 vcc, 1, v222
	s_and_saveexec_b64 s[8:9], vcc
	s_cbranch_execz .Lg1_nba
	s_barrier
.Lg1_nba:
	s_or_b64 exec, exec, s[8:9]
	s_waitcnt vmcnt(28)
	s_barrier
	s_waitcnt vmcnt(24)
	s_branch .Lg1_zero

; #define STAGE(P, BASE, br, kt) do { const long _g = (long)(br) * K + (long)(kt) * 64; \
;     _Pragma("unroll") for (int _i = 0; _i < 2; ++_i) { const int _b = tidx * 16 + _i * 8192; int _r, _c; stage_rc8(_b, _r, _c); \
;       __builtin_amdgcn_global_load_lds((const unsigned*)(BASE + _g + (long)_r * K + _c), (LAS unsigned*)((LAS char*)(P) + _b), 16, 0, 0); } } while (0)
; #define LDA(dst, b, h) _Pragma("unroll") for (int m = 0; m < 4; ++m) _Pragma("unroll") for (int k = 0; k < 2; ++k) \
;     dst[m][k] = *reinterpret_cast<const bf16x8*>((const char*)SA(b, h) + lds_byte8(wr * 64 + m * 16 + fr, k * 32 + fq * 8))
; #define LDB(dst, b, h) _Pragma("unroll") for (int n = 0; n < 2; ++n) _Pragma("unroll") for (int k = 0; k < 2; ++k) \
;     dst[n][k] = *reinterpret_cast<const bf16x8*>((const char*)SB(b, h) + lds_byte8(wc * 32 + n * 16 + fr, k * 32 + fq * 8))
; #define MMA(ai, bj, At_, Bt_) do { __builtin_amdgcn_s_setprio(1); \
;     _Pragma("unroll") for (int m = 0; m < 4; ++m) _Pragma("unroll") for (int n = 0; n < 2; ++n) _Pragma("unroll") for (int k = 0; k < 2; ++k) \
;       acc[ai][bj][m][n] = MFMA16(Bt_[n][k], At_[m][k], acc[ai][bj][m][n]); \
;     __builtin_amdgcn_s_setprio(0); } while (0)
; #define WAIT_V(n) asm volatile("s_waitcnt vmcnt(" #n ")" ::: "memory")
; #define WAIT_L(n) asm volatile("s_waitcnt lgkmcnt(" #n ")" ::: "memory")
; #define BAR __builtin_amdgcn_s_barrier()
; #define SCHED __builtin_amdgcn_sched_barrier(0)
; template <class FL, class FS>
; DI void gemm8_tile(char* shmc, const bf16_t* __restrict__ A, const bf16_t* __restrict__ Bt, const int K, const int brow, const int bcol, FL fl, FS fs) {
;     ...
;         for (int n = 0; n < 2; ++n) acc[a][b][m][n] = (f32x4){0.f, 0.f, 0.f, 0.f};
;   bf16x8 At[4][2], B0[2][2], B1[2][2];
;   const int nt = K / 64;
;   STAGE(SB(0, 0), Bt, bcol, 0); STAGE(SA(0, 0), A, brow, 0);
;   STAGE(SB(0, 1), Bt, bcol + HALF, 0); STAGE(SA(0, 1), A, brow + HALF, 0);
;   if (wr == 1) BAR;
;   WAIT_V(4); BAR;
;   STAGE(SB(1, 0), Bt, bcol, 1); STAGE(SA(1, 0), A, brow, 1); STAGE(SB(1, 1), Bt, bcol + HALF, 1);
;   WAIT_V(6); BAR;
;   for (int t = 0; t < nt - 2; t += 2) {
;     LDB(B0, 0, 0); SCHED; LDA(At, 0, 0); STAGE(SA(1, 1), A, brow + HALF, t + 1);
;     WAIT_L(8); BAR; WAIT_L(0); MMA(0, 0, At, B0); BAR; SCHED;
.Lg1_nbb:
	s_or_b64 exec, exec, s[8:9]
	s_waitcnt vmcnt(12)
	s_barrier
	s_waitcnt vmcnt(8)
.Lg1_zero:
	v_mov_b32_e32 v0, 0
	v_mov_b32_e32 v1, v0
	v_mov_b32_e32 v2, v0
	v_mov_b32_e32 v3, v0
	v_mov_b32_e32 v4, v0
	v_mov_b32_e32 v5, v0
	v_mov_b32_e32 v6, v0
	v_mov_b32_e32 v7, v0
	v_mov_b32_e32 v8, v0
	v_mov_b32_e32 v9, v0
	v_mov_b32_e32 v10, v0
	v_mov_b32_e32 v11, v0
	v_mov_b32_e32 v12, v0
	v_mov_b32_e32 v13, v0
	v_mov_b32_e32 v14, v0
	v_mov_b32_e32 v15, v0
	v_mov_b32_e32 v16, v0
	v_mov_b32_e32 v17, v0
	v_mov_b32_e32 v18, v0
	v_mov_b32_e32 v19, v0
	v_mov_b32_e32 v20, v0
	v_mov_b32_e32 v21, v0
	v_mov_b32_e32 v22, v0
	v_mov_b32_e32 v23, v0
	v_mov_b32_e32 v24, v0
	v_mov_b32_e32 v25, v0
	v_mov_b32_e32 v26, v0
	v_mov_b32_e32 v27, v0
	v_mov_b32_e32 v28, v0
	v_mov_b32_e32 v29, v0
	v_mov_b32_e32 v30, v0
	v_mov_b32_e32 v31, v0
	v_mov_b32_e32 v32, v0
	v_mov_b32_e32 v33, v0
	v_mov_b32_e32 v34, v0
	v_mov_b32_e32 v35, v0
	v_mov_b32_e32 v36, v0
	v_mov_b32_e32 v37, v0
	v_mov_b32_e32 v38, v0
	v_mov_b32_e32 v39, v0
	v_mov_b32_e32 v40, v0
	v_mov_b32_e32 v41, v0
	v_mov_b32_e32 v42, v0
	v_mov_b32_e32 v43, v0
	v_mov_b32_e32 v44, v0
	v_mov_b32_e32 v45, v0
	v_mov_b32_e32 v46, v0
	v_mov_b32_e32 v47, v0
	v_mov_b32_e32 v48, v0
	v_mov_b32_e32 v49, v0
	v_mov_b32_e32 v50, v0
	v_mov_b32_e32 v51, v0
	v_mov_b32_e32 v52, v0
	v_mov_b32_e32 v53, v0
	v_mov_b32_e32 v54, v0
	v_mov_b32_e32 v55, v0
	v_mov_b32_e32 v56, v0
	v_mov_b32_e32 v57, v0
	v_mov_b32_e32 v58, v0
	v_mov_b32_e32 v59, v0
	v_mov_b32_e32 v60, v0
	v_mov_b32_e32 v61, v0
	v_mov_b32_e32 v62, v0
	v_mov_b32_e32 v63, v0
	v_mov_b32_e32 v64, v0
	v_mov_b32_e32 v65, v0
	v_mov_b32_e32 v66, v0
	v_mov_b32_e32 v67, v0
	v_mov_b32_e32 v68, v0
	v_mov_b32_e32 v69, v0
	v_mov_b32_e32 v70, v0
	v_mov_b32_e32 v71, v0
	v_mov_b32_e32 v72, v0
	v_mov_b32_e32 v73, v0
	v_mov_b32_e32 v74, v0
	v_mov_b32_e32 v75, v0
	v_mov_b32_e32 v76, v0
	v_mov_b32_e32 v77, v0
	v_mov_b32_e32 v78, v0
	v_mov_b32_e32 v79, v0
	v_mov_b32_e32 v80, v0
	v_mov_b32_e32 v81, v0
	v_mov_b32_e32 v82, v0
	v_mov_b32_e32 v83, v0
	v_mov_b32_e32 v84, v0
	v_mov_b32_e32 v85, v0
	v_mov_b32_e32 v86, v0
	v_mov_b32_e32 v87, v0
	v_mov_b32_e32 v88, v0
	v_mov_b32_e32 v89, v0
	v_mov_b32_e32 v90, v0
	v_mov_b32_e32 v91, v0
	v_mov_b32_e32 v92, v0
	v_mov_b32_e32 v93, v0
	v_mov_b32_e32 v94, v0
	v_mov_b32_e32 v95, v0
	v_mov_b32_e32 v96, v0
	v_mov_b32_e32 v97, v0
	v_mov_b32_e32 v98, v0
	v_mov_b32_e32 v99, v0
	v_mov_b32_e32 v100, v0
	v_mov_b32_e32 v101, v0
	v_mov_b32_e32 v102, v0
	v_mov_b32_e32 v103, v0
	v_mov_b32_e32 v104, v0
	v_mov_b32_e32 v105, v0
	v_mov_b32_e32 v106, v0
	v_mov_b32_e32 v107, v0
	v_mov_b32_e32 v108, v0
	v_mov_b32_e32 v109, v0
	v_mov_b32_e32 v110, v0
	v_mov_b32_e32 v111, v0
	v_mov_b32_e32 v112, v0
	v_mov_b32_e32 v113, v0
	v_mov_b32_e32 v114, v0
	v_mov_b32_e32 v115, v0
	v_mov_b32_e32 v116, v0
	v_mov_b32_e32 v117, v0
	v_mov_b32_e32 v118, v0
	v_mov_b32_e32 v119, v0
	v_mov_b32_e32 v120, v0
	v_mov_b32_e32 v121, v0
	v_mov_b32_e32 v122, v0
	v_mov_b32_e32 v123, v0
	v_mov_b32_e32 v124, v0
	v_mov_b32_e32 v125, v0
	v_mov_b32_e32 v126, v0
	v_mov_b32_e32 v127, v0
	s_mov_b32 s0, -2
	s_barrier
.LBB0_202:
	ds_read_b128 v[172:175], v170
	ds_read_b128 v[176:179], v170 offset:1024
	ds_read_b128 v[184:187], v170 offset:2048
	ds_read_b128 v[188:191], v170 offset:3072
	v_lshl_add_u64 v[180:181], s[12:13], 0, v[138:139]
	v_readfirstlane_b32 s1, v169
	v_lshl_add_u64 v[224:225], v[180:181], 0, s[22:23]
	s_mov_b32 m0, s1
	v_lshl_add_u64 v[240:241], s[12:13], 0, v[140:141]
	v_readfirstlane_b32 s1, v168
	ds_read_b128 v[192:195], v152
	ds_read_b128 v[196:199], v152 offset:1024
	ds_read_b128 v[200:203], v151
	ds_read_b128 v[204:207], v151 offset:1024
	ds_read_b128 v[208:211], v150
	ds_read_b128 v[212:215], v150 offset:1024
	ds_read_b128 v[216:219], v148
	ds_read_b128 v[220:223], v148 offset:1024
	s_cmp_eq_u32 s0, -2
	s_cbranch_scc1 .Lg1_p1skip
	global_load_lds_dwordx4 v[224:225], off
	v_lshl_add_u64 v[224:225], v[240:241], 0, s[22:23]
	s_mov_b32 m0, s1
	s_nop 0
	global_load_lds_dwordx4 v[224:225], off
.Lg1_p1skip:
	s_waitcnt lgkmcnt(8)
	s_barrier
	s_waitcnt lgkmcnt(0)
	s_setprio 1
	s_waitcnt lgkmcnt(0)
	v_mfma_f32_16x16x32_bf16 v[124:127], v[172:175], v[192:195], v[124:127]
	v_mfma_f32_16x16x32_bf16 v[120:123], v[184:187], v[192:195], v[120:123]
	v_mfma_f32_16x16x32_bf16 v[116:119], v[172:175], v[200:203], v[116:119]
	v_mfma_f32_16x16x32_bf16 v[112:115], v[184:187], v[200:203], v[112:115]
	v_mfma_f32_16x16x32_bf16 v[108:111], v[172:175], v[208:211], v[108:111]
	v_mfma_f32_16x16x32_bf16 v[104:107], v[184:187], v[208:211], v[104:107]
	v_mfma_f32_16x16x32_bf16 v[100:103], v[172:175], v[216:219], v[100:103]
	v_mfma_f32_16x16x32_bf16 v[96:99], v[184:187], v[216:219], v[96:99]
	v_mfma_f32_16x16x32_bf16 v[124:127], v[176:179], v[196:199], v[124:127]
	v_mfma_f32_16x16x32_bf16 v[120:123], v[188:191], v[196:199], v[120:123]
	v_mfma_f32_16x16x32_bf16 v[116:119], v[176:179], v[204:207], v[116:119]
	v_mfma_f32_16x16x32_bf16 v[112:115], v[188:191], v[204:207], v[112:115]
	v_mfma_f32_16x16x32_bf16 v[108:111], v[176:179], v[212:215], v[108:111]
	v_mfma_f32_16x16x32_bf16 v[104:107], v[188:191], v[212:215], v[104:107]
	v_mfma_f32_16x16x32_bf16 v[100:103], v[176:179], v[220:223], v[100:103]
	v_mfma_f32_16x16x32_bf16 v[96:99], v[188:191], v[220:223], v[96:99]
	s_setprio 0
	s_barrier
	v_lshl_add_u64 v[242:243], s[12:13], 0, v[134:135]
	v_readfirstlane_b32 s1, v149
	v_lshl_add_u64 v[244:245], v[242:243], 0, s[24:25]
	s_mov_b32 m0, s1
	ds_read_b128 v[224:227], v166
	ds_read_b128 v[228:231], v166 offset:1024
	ds_read_b128 v[232:235], v166 offset:2048
	ds_read_b128 v[236:239], v166 offset:3072
	global_load_lds_dwordx4 v[244:245], off
	v_lshl_add_u64 v[244:245], s[12:13], 0, v[136:137]
	v_readfirstlane_b32 s1, v155
	v_lshl_add_u64 v[246:247], v[244:245], 0, s[24:25]
	s_mov_b32 m0, s1
	s_nop 0
	global_load_lds_dwordx4 v[246:247], off
	s_barrier
; #define STAGE(P, BASE, br, kt) do { const long _g = (long)(br) * K + (long)(kt) * 64; \
;     _Pragma("unroll") for (int _i = 0; _i < 2; ++_i) { const int _b = tidx * 16 + _i * 8192; int _r, _c; stage_rc8(_b, _r, _c); \
;       __builtin_amdgcn_global_load_lds((const unsigned*)(BASE + _g + (long)_r * K + _c), (LAS unsigned*)((LAS char*)(P) + _b), 16, 0, 0); } } while (0)
; #define LDA(dst, b, h) _Pragma("unroll") for (int m = 0; m < 4; ++m) _Pragma("unroll") for (int k = 0; k < 2; ++k) \
;     dst[m][k] = *reinterpret_cast<const bf16x8*>((const char*)SA(b, h) + lds_byte8(wr * 64 + m * 16 + fr, k * 32 + fq * 8))
; #define LDB(dst, b, h) _Pragma("unroll") for (int n = 0; n < 2; ++n) _Pragma("unroll") for (int k = 0; k < 2; ++k) \
;     dst[n][k] = *reinterpret_cast<const bf16x8*>((const char*)SB(b, h) + lds_byte8(wc * 32 + n * 16 + fr, k * 32 + fq * 8))
; #define MMA(ai, bj, At_, Bt_) do { __builtin_amdgcn_s_setprio(1); \
;     _Pragma("unroll") for (int m = 0; m < 4; ++m) _Pragma("unroll") for (int n = 0; n < 2; ++n) _Pragma("unroll") for (int k = 0; k < 2; ++k) \
;       acc[ai][bj][m][n] = MFMA16(Bt_[n][k], At_[m][k], acc[ai][bj][m][n]); \
;     __builtin_amdgcn_s_setprio(0); } while (0)
; #define WAIT_V(n) asm volatile("s_waitcnt vmcnt(" #n ")" ::: "memory")
; #define WAIT_L(n) asm volatile("s_waitcnt lgkmcnt(" #n ")" ::: "memory")
; #define BAR __builtin_amdgcn_s_barrier()
; #define SCHED __builtin_amdgcn_sched_barrier(0)
; template <class FL, class FS>
; DI void gemm8_tile(char* shmc, const bf16_t* __restrict__ A, const bf16_t* __restrict__ Bt, const int K, const int brow, const int bcol, FL fl, FS fs) {
;     ...
;     LDB(B1, 0, 1); STAGE(SB(0, 0), Bt, bcol, t + 2);
;     BAR; WAIT_L(0); MMA(0, 1, At, B1); BAR;
;     LDA(At, 0, 1); STAGE(SA(0, 0), A, brow, t + 2);
;     BAR; WAIT_L(0); MMA(1, 0, At, B0); BAR; SCHED;
;     STAGE(SB(0, 1), Bt, bcol + HALF, t + 2);
;     WAIT_V(6); BAR; MMA(1, 1, At, B1); BAR;
;     LDB(B0, 1, 0); SCHED; LDA(At, 1, 0); STAGE(SA(0, 1), A, brow + HALF, t + 2);
;     WAIT_L(8); BAR; WAIT_L(0); MMA(0, 0, At, B0); BAR; SCHED;
	s_waitcnt lgkmcnt(0)
	s_setprio 1
	s_waitcnt lgkmcnt(0)
	v_mfma_f32_16x16x32_bf16 v[92:95], v[224:227], v[192:195], v[92:95]
	v_mfma_f32_16x16x32_bf16 v[88:91], v[232:235], v[192:195], v[88:91]
	v_mfma_f32_16x16x32_bf16 v[84:87], v[224:227], v[200:203], v[84:87]
	v_mfma_f32_16x16x32_bf16 v[80:83], v[232:235], v[200:203], v[80:83]
	v_mfma_f32_16x16x32_bf16 v[76:79], v[224:227], v[208:211], v[76:79]
	v_mfma_f32_16x16x32_bf16 v[72:75], v[232:235], v[208:211], v[72:75]
	v_mfma_f32_16x16x32_bf16 v[68:71], v[224:227], v[216:219], v[68:71]
	v_mfma_f32_16x16x32_bf16 v[64:67], v[232:235], v[216:219], v[64:67]
	v_mfma_f32_16x16x32_bf16 v[92:95], v[228:231], v[196:199], v[92:95]
	v_mfma_f32_16x16x32_bf16 v[88:91], v[236:239], v[196:199], v[88:91]
	v_mfma_f32_16x16x32_bf16 v[84:87], v[228:231], v[204:207], v[84:87]
	v_mfma_f32_16x16x32_bf16 v[80:83], v[236:239], v[204:207], v[80:83]
	v_mfma_f32_16x16x32_bf16 v[76:79], v[228:231], v[212:215], v[76:79]
	v_mfma_f32_16x16x32_bf16 v[72:75], v[236:239], v[212:215], v[72:75]
	v_mfma_f32_16x16x32_bf16 v[68:71], v[228:231], v[220:223], v[68:71]
	v_mfma_f32_16x16x32_bf16 v[64:67], v[236:239], v[220:223], v[64:67]
	s_setprio 0
	v_readfirstlane_b32 s1, v147
	v_lshl_add_u64 v[246:247], v[180:181], 0, s[26:27]
	s_mov_b32 m0, s1
	v_readfirstlane_b32 s1, v153
	s_barrier
	ds_read_b128 v[192:195], v152 offset:16384
	ds_read_b128 v[196:199], v152 offset:17408
	ds_read_b128 v[200:203], v151 offset:16384
	ds_read_b128 v[204:207], v151 offset:17408
	ds_read_b128 v[208:211], v150 offset:16384
	ds_read_b128 v[212:215], v150 offset:17408
	ds_read_b128 v[216:219], v148 offset:16384
	ds_read_b128 v[220:223], v148 offset:17408
	global_load_lds_dwordx4 v[246:247], off
	v_lshl_add_u64 v[246:247], v[240:241], 0, s[26:27]
	s_mov_b32 m0, s1
	s_nop 0
	global_load_lds_dwordx4 v[246:247], off
	s_barrier
	s_waitcnt lgkmcnt(0)
	s_setprio 1
	s_waitcnt lgkmcnt(0)
	v_mfma_f32_16x16x32_bf16 v[60:63], v[172:175], v[192:195], v[60:63]
	v_mfma_f32_16x16x32_bf16 v[56:59], v[184:187], v[192:195], v[56:59]
	v_mfma_f32_16x16x32_bf16 v[52:55], v[172:175], v[200:203], v[52:55]
	v_mfma_f32_16x16x32_bf16 v[48:51], v[184:187], v[200:203], v[48:51]
	v_mfma_f32_16x16x32_bf16 v[44:47], v[172:175], v[208:211], v[44:47]
	v_mfma_f32_16x16x32_bf16 v[40:43], v[184:187], v[208:211], v[40:43]
	v_mfma_f32_16x16x32_bf16 v[36:39], v[172:175], v[216:219], v[36:39]
	v_mfma_f32_16x16x32_bf16 v[32:35], v[184:187], v[216:219], v[32:35]
	v_mfma_f32_16x16x32_bf16 v[60:63], v[176:179], v[196:199], v[60:63]
	v_mfma_f32_16x16x32_bf16 v[56:59], v[188:191], v[196:199], v[56:59]
	v_mfma_f32_16x16x32_bf16 v[52:55], v[176:179], v[204:207], v[52:55]
	v_mfma_f32_16x16x32_bf16 v[48:51], v[188:191], v[204:207], v[48:51]
	v_mfma_f32_16x16x32_bf16 v[44:47], v[176:179], v[212:215], v[44:47]
	v_mfma_f32_16x16x32_bf16 v[40:43], v[188:191], v[212:215], v[40:43]
	v_mfma_f32_16x16x32_bf16 v[36:39], v[176:179], v[220:223], v[36:39]
	v_mfma_f32_16x16x32_bf16 v[32:35], v[188:191], v[220:223], v[32:35]
	s_setprio 0
	s_barrier
	v_readfirstlane_b32 s1, v157
	v_lshl_add_u64 v[172:173], v[242:243], 0, s[28:29]
	s_mov_b32 m0, s1
	v_readfirstlane_b32 s1, v158
	global_load_lds_dwordx4 v[172:173], off
	v_lshl_add_u64 v[172:173], v[244:245], 0, s[28:29]
	s_mov_b32 m0, s1
	s_nop 0
	global_load_lds_dwordx4 v[172:173], off
	s_cmp_eq_u32 s0, -2
	s_cselect_b32 s1, s98, 0
	s_cmp_lg_u32 s1, 0
	s_cbranch_scc1 .Lg1_w22
	s_waitcnt vmcnt(6)
.Lg1_wd:
	s_barrier
	s_setprio 1
	v_mfma_f32_16x16x32_bf16 v[28:31], v[224:227], v[192:195], v[28:31]
	v_mfma_f32_16x16x32_bf16 v[24:27], v[232:235], v[192:195], v[24:27]
	v_mfma_f32_16x16x32_bf16 v[20:23], v[224:227], v[200:203], v[20:23]
	v_mfma_f32_16x16x32_bf16 v[16:19], v[232:235], v[200:203], v[16:19]
	v_mfma_f32_16x16x32_bf16 v[12:15], v[224:227], v[208:211], v[12:15]
	v_mfma_f32_16x16x32_bf16 v[8:11], v[232:235], v[208:211], v[8:11]
	v_mfma_f32_16x16x32_bf16 v[4:7], v[224:227], v[216:219], v[4:7]
	v_mfma_f32_16x16x32_bf16 v[0:3], v[232:235], v[216:219], v[0:3]
	v_mfma_f32_16x16x32_bf16 v[28:31], v[228:231], v[196:199], v[28:31]
	v_mfma_f32_16x16x32_bf16 v[24:27], v[236:239], v[196:199], v[24:27]
	v_mfma_f32_16x16x32_bf16 v[20:23], v[228:231], v[204:207], v[20:23]
	v_mfma_f32_16x16x32_bf16 v[16:19], v[236:239], v[204:207], v[16:19]
	v_mfma_f32_16x16x32_bf16 v[12:15], v[228:231], v[212:215], v[12:15]
	v_mfma_f32_16x16x32_bf16 v[8:11], v[236:239], v[212:215], v[8:11]
	v_mfma_f32_16x16x32_bf16 v[4:7], v[228:231], v[220:223], v[4:7]
	v_mfma_f32_16x16x32_bf16 v[0:3], v[236:239], v[220:223], v[0:3]
	s_setprio 0
	s_barrier
	ds_read_b128 v[172:175], v156
	ds_read_b128 v[176:179], v156 offset:1024
	ds_read_b128 v[184:187], v156 offset:2048
	ds_read_b128 v[188:191], v156 offset:3072
	v_readfirstlane_b32 s1, v159
	v_lshl_add_u64 v[224:225], v[180:181], 0, s[30:31]
	s_mov_b32 m0, s1
	v_readfirstlane_b32 s1, v160
	ds_read_b128 v[192:195], v152 offset:32768
	ds_read_b128 v[196:199], v152 offset:33792
	ds_read_b128 v[200:203], v151 offset:32768
	ds_read_b128 v[204:207], v151 offset:33792
	ds_read_b128 v[208:211], v150 offset:32768
	ds_read_b128 v[212:215], v150 offset:33792
	ds_read_b128 v[216:219], v148 offset:32768
	ds_read_b128 v[220:223], v148 offset:33792
	global_load_lds_dwordx4 v[224:225], off
	v_lshl_add_u64 v[224:225], v[240:241], 0, s[30:31]
	s_mov_b32 m0, s1
	s_nop 0
	global_load_lds_dwordx4 v[224:225], off
	s_waitcnt lgkmcnt(8)
	s_barrier
; #define STAGE(P, BASE, br, kt) do { const long _g = (long)(br) * K + (long)(kt) * 64; \
;     _Pragma("unroll") for (int _i = 0; _i < 2; ++_i) { const int _b = tidx * 16 + _i * 8192; int _r, _c; stage_rc8(_b, _r, _c); \
;       __builtin_amdgcn_global_load_lds((const unsigned*)(BASE + _g + (long)_r * K + _c), (LAS unsigned*)((LAS char*)(P) + _b), 16, 0, 0); } } while (0)
; #define LDA(dst, b, h) _Pragma("unroll") for (int m = 0; m < 4; ++m) _Pragma("unroll") for (int k = 0; k < 2; ++k) \
;     dst[m][k] = *reinterpret_cast<const bf16x8*>((const char*)SA(b, h) + lds_byte8(wr * 64 + m * 16 + fr, k * 32 + fq * 8))
; #define LDB(dst, b, h) _Pragma("unroll") for (int n = 0; n < 2; ++n) _Pragma("unroll") for (int k = 0; k < 2; ++k) \
;     dst[n][k] = *reinterpret_cast<const bf16x8*>((const char*)SB(b, h) + lds_byte8(wc * 32 + n * 16 + fr, k * 32 + fq * 8))
; #define MMA(ai, bj, At_, Bt_) do { __builtin_amdgcn_s_setprio(1); \
;     _Pragma("unroll") for (int m = 0; m < 4; ++m) _Pragma("unroll") for (int n = 0; n < 2; ++n) _Pragma("unroll") for (int k = 0; k < 2; ++k) \
;       acc[ai][bj][m][n] = MFMA16(Bt_[n][k], At_[m][k], acc[ai][bj][m][n]); \
;     __builtin_amdgcn_s_setprio(0); } while (0)
; #define WAIT_V(n) asm volatile("s_waitcnt vmcnt(" #n ")" ::: "memory")
; #define WAIT_L(n) asm volatile("s_waitcnt lgkmcnt(" #n ")" ::: "memory")
; #define BAR __builtin_amdgcn_s_barrier()
; #define SCHED __builtin_amdgcn_sched_barrier(0)
; template <class FL, class FS>
; DI void gemm8_tile(char* shmc, const bf16_t* __restrict__ A, const bf16_t* __restrict__ Bt, const int K, const int brow, const int bcol, FL fl, FS fs) {
;     ...
;     LDB(B0, 1, 0); SCHED; LDA(At, 1, 0); STAGE(SA(0, 1), A, brow + HALF, t + 2);
;     WAIT_L(8); BAR; WAIT_L(0); MMA(0, 0, At, B0); BAR; SCHED;
;     LDB(B1, 1, 1); STAGE(SB(1, 0), Bt, bcol, t + 3);
;     BAR; WAIT_L(0); MMA(0, 1, At, B1); BAR;
;     LDA(At, 1, 1); STAGE(SA(1, 0), A, brow, t + 3);
;     BAR; WAIT_L(0); MMA(1, 0, At, B0); BAR; SCHED;
;     STAGE(SB(1, 1), Bt, bcol + HALF, t + 3);
;     WAIT_V(6); BAR; MMA(1, 1, At, B1); BAR;
	s_waitcnt lgkmcnt(0)
	s_setprio 1
	s_waitcnt lgkmcnt(0)
	v_mfma_f32_16x16x32_bf16 v[124:127], v[172:175], v[192:195], v[124:127]
	v_mfma_f32_16x16x32_bf16 v[120:123], v[184:187], v[192:195], v[120:123]
	v_mfma_f32_16x16x32_bf16 v[116:119], v[172:175], v[200:203], v[116:119]
	v_mfma_f32_16x16x32_bf16 v[112:115], v[184:187], v[200:203], v[112:115]
	v_mfma_f32_16x16x32_bf16 v[108:111], v[172:175], v[208:211], v[108:111]
	v_mfma_f32_16x16x32_bf16 v[104:107], v[184:187], v[208:211], v[104:107]
	v_mfma_f32_16x16x32_bf16 v[100:103], v[172:175], v[216:219], v[100:103]
	v_mfma_f32_16x16x32_bf16 v[96:99], v[184:187], v[216:219], v[96:99]
	v_mfma_f32_16x16x32_bf16 v[124:127], v[176:179], v[196:199], v[124:127]
	v_mfma_f32_16x16x32_bf16 v[120:123], v[188:191], v[196:199], v[120:123]
	v_mfma_f32_16x16x32_bf16 v[116:119], v[176:179], v[204:207], v[116:119]
	v_mfma_f32_16x16x32_bf16 v[112:115], v[188:191], v[204:207], v[112:115]
	v_mfma_f32_16x16x32_bf16 v[108:111], v[176:179], v[212:215], v[108:111]
	v_mfma_f32_16x16x32_bf16 v[104:107], v[188:191], v[212:215], v[104:107]
	v_mfma_f32_16x16x32_bf16 v[100:103], v[176:179], v[220:223], v[100:103]
	v_mfma_f32_16x16x32_bf16 v[96:99], v[188:191], v[220:223], v[96:99]
	s_setprio 0
	s_barrier
	v_readfirstlane_b32 s1, v161
	v_lshl_add_u64 v[246:247], v[242:243], 0, s[34:35]
	s_mov_b32 m0, s1
	v_readfirstlane_b32 s1, v162
	ds_read_b128 v[224:227], v154
	ds_read_b128 v[228:231], v154 offset:1024
	ds_read_b128 v[232:235], v154 offset:2048
	ds_read_b128 v[236:239], v154 offset:3072
	global_load_lds_dwordx4 v[246:247], off
	v_lshl_add_u64 v[246:247], v[244:245], 0, s[34:35]
	s_mov_b32 m0, s1
	s_nop 0
	global_load_lds_dwordx4 v[246:247], off
	s_barrier
	s_waitcnt lgkmcnt(0)
	s_setprio 1
	s_waitcnt lgkmcnt(0)
	v_mfma_f32_16x16x32_bf16 v[92:95], v[224:227], v[192:195], v[92:95]
	v_mfma_f32_16x16x32_bf16 v[88:91], v[232:235], v[192:195], v[88:91]
	v_mfma_f32_16x16x32_bf16 v[84:87], v[224:227], v[200:203], v[84:87]
	v_mfma_f32_16x16x32_bf16 v[80:83], v[232:235], v[200:203], v[80:83]
	v_mfma_f32_16x16x32_bf16 v[76:79], v[224:227], v[208:211], v[76:79]
	v_mfma_f32_16x16x32_bf16 v[72:75], v[232:235], v[208:211], v[72:75]
	v_mfma_f32_16x16x32_bf16 v[68:71], v[224:227], v[216:219], v[68:71]
	v_mfma_f32_16x16x32_bf16 v[64:67], v[232:235], v[216:219], v[64:67]
	v_mfma_f32_16x16x32_bf16 v[92:95], v[228:231], v[196:199], v[92:95]
	v_mfma_f32_16x16x32_bf16 v[88:91], v[236:239], v[196:199], v[88:91]
	v_mfma_f32_16x16x32_bf16 v[84:87], v[228:231], v[204:207], v[84:87]
	v_mfma_f32_16x16x32_bf16 v[80:83], v[236:239], v[204:207], v[80:83]
	v_mfma_f32_16x16x32_bf16 v[76:79], v[228:231], v[212:215], v[76:79]
	v_mfma_f32_16x16x32_bf16 v[72:75], v[236:239], v[212:215], v[72:75]
	v_mfma_f32_16x16x32_bf16 v[68:71], v[228:231], v[220:223], v[68:71]
	v_mfma_f32_16x16x32_bf16 v[64:67], v[236:239], v[220:223], v[64:67]
	s_setprio 0
	v_readfirstlane_b32 s1, v163
	v_lshl_add_u64 v[180:181], v[180:181], 0, s[36:37]
	s_mov_b32 m0, s1
	v_readfirstlane_b32 s1, v164
	s_barrier
	ds_read_b128 v[192:195], v152 offset:49152
	ds_read_b128 v[196:199], v152 offset:50176
	ds_read_b128 v[200:203], v151 offset:49152
	ds_read_b128 v[204:207], v151 offset:50176
	ds_read_b128 v[208:211], v150 offset:49152
	ds_read_b128 v[212:215], v150 offset:50176
	ds_read_b128 v[216:219], v148 offset:49152
	ds_read_b128 v[220:223], v148 offset:50176
	global_load_lds_dwordx4 v[180:181], off
	v_lshl_add_u64 v[180:181], v[240:241], 0, s[36:37]
	s_mov_b32 m0, s1
	s_nop 0
	global_load_lds_dwordx4 v[180:181], off
	s_barrier
	s_waitcnt lgkmcnt(0)
	s_setprio 1
	s_waitcnt lgkmcnt(0)
	v_mfma_f32_16x16x32_bf16 v[60:63], v[172:175], v[192:195], v[60:63]
	v_mfma_f32_16x16x32_bf16 v[56:59], v[184:187], v[192:195], v[56:59]
	v_mfma_f32_16x16x32_bf16 v[52:55], v[172:175], v[200:203], v[52:55]
	v_mfma_f32_16x16x32_bf16 v[48:51], v[184:187], v[200:203], v[48:51]
	v_mfma_f32_16x16x32_bf16 v[44:47], v[172:175], v[208:211], v[44:47]
	v_mfma_f32_16x16x32_bf16 v[40:43], v[184:187], v[208:211], v[40:43]
	v_mfma_f32_16x16x32_bf16 v[36:39], v[172:175], v[216:219], v[36:39]
	v_mfma_f32_16x16x32_bf16 v[32:35], v[184:187], v[216:219], v[32:35]
	v_mfma_f32_16x16x32_bf16 v[60:63], v[176:179], v[196:199], v[60:63]
	v_mfma_f32_16x16x32_bf16 v[56:59], v[188:191], v[196:199], v[56:59]
	v_mfma_f32_16x16x32_bf16 v[52:55], v[176:179], v[204:207], v[52:55]
	v_mfma_f32_16x16x32_bf16 v[48:51], v[188:191], v[204:207], v[48:51]
	v_mfma_f32_16x16x32_bf16 v[44:47], v[176:179], v[212:215], v[44:47]
	v_mfma_f32_16x16x32_bf16 v[40:43], v[188:191], v[212:215], v[40:43]
	v_mfma_f32_16x16x32_bf16 v[36:39], v[176:179], v[220:223], v[36:39]
	v_mfma_f32_16x16x32_bf16 v[32:35], v[188:191], v[220:223], v[32:35]
	s_setprio 0
	s_barrier
	v_readfirstlane_b32 s1, v165
	v_lshl_add_u64 v[172:173], v[242:243], 0, s[38:39]
	s_mov_b32 m0, s1
	v_readfirstlane_b32 s1, v167
	global_load_lds_dwordx4 v[172:173], off
	v_lshl_add_u64 v[172:173], v[244:245], 0, s[38:39]
	s_mov_b32 m0, s1
	s_nop 0
	global_load_lds_dwordx4 v[172:173], off
	s_waitcnt vmcnt(6)
	s_barrier
; #define STAGE(P, BASE, br, kt) do { const long _g = (long)(br) * K + (long)(kt) * 64; \
;     _Pragma("unroll") for (int _i = 0; _i < 2; ++_i) { const int _b = tidx * 16 + _i * 8192; int _r, _c; stage_rc8(_b, _r, _c); \
;       __builtin_amdgcn_global_load_lds((const unsigned*)(BASE + _g + (long)_r * K + _c), (LAS unsigned*)((LAS char*)(P) + _b), 16, 0, 0); } } while (0)
; #define LDA(dst, b, h) _Pragma("unroll") for (int m = 0; m < 4; ++m) _Pragma("unroll") for (int k = 0; k < 2; ++k) \
;     dst[m][k] = *reinterpret_cast<const bf16x8*>((const char*)SA(b, h) + lds_byte8(wr * 64 + m * 16 + fr, k * 32 + fq * 8))
; #define LDB(dst, b, h) _Pragma("unroll") for (int n = 0; n < 2; ++n) _Pragma("unroll") for (int k = 0; k < 2; ++k) \
;     dst[n][k] = *reinterpret_cast<const bf16x8*>((const char*)SB(b, h) + lds_byte8(wc * 32 + n * 16 + fr, k * 32 + fq * 8))
; #define MMA(ai, bj, At_, Bt_) do { __builtin_amdgcn_s_setprio(1); \
;     _Pragma("unroll") for (int m = 0; m < 4; ++m) _Pragma("unroll") for (int n = 0; n < 2; ++n) _Pragma("unroll") for (int k = 0; k < 2; ++k) \
;       acc[ai][bj][m][n] = MFMA16(Bt_[n][k], At_[m][k], acc[ai][bj][m][n]); \
;     __builtin_amdgcn_s_setprio(0); } while (0)
; #define WAIT_V(n) asm volatile("s_waitcnt vmcnt(" #n ")" ::: "memory")
; #define WAIT_L(n) asm volatile("s_waitcnt lgkmcnt(" #n ")" ::: "memory")
; #define BAR __builtin_amdgcn_s_barrier()
; template <class FL, class FS>
; DI void gemm8_tile(char* shmc, const bf16_t* __restrict__ A, const bf16_t* __restrict__ Bt, const int K, const int brow, const int bcol, FL fl, FS fs) {
;     ...
;     WAIT_V(6); BAR; MMA(1, 1, At, B1); BAR;
;   }
;   { LDB(B0, 0, 0); LDA(At, 0, 0); STAGE(SA(1, 1), A, brow + HALF, nt - 1);
;     BAR; WAIT_L(0); MMA(0, 0, At, B0); BAR;
;     LDB(B1, 0, 1); BAR; WAIT_L(0); MMA(0, 1, At, B1); BAR;
;     LDA(At, 0, 1); WAIT_V(4); BAR; WAIT_L(0); MMA(1, 0, At, B0); MMA(1, 1, At, B1); BAR; }
	s_setprio 1
	v_mfma_f32_16x16x32_bf16 v[28:31], v[224:227], v[192:195], v[28:31]
	v_mfma_f32_16x16x32_bf16 v[24:27], v[232:235], v[192:195], v[24:27]
	v_mfma_f32_16x16x32_bf16 v[20:23], v[224:227], v[200:203], v[20:23]
	v_mfma_f32_16x16x32_bf16 v[16:19], v[232:235], v[200:203], v[16:19]
	v_mfma_f32_16x16x32_bf16 v[12:15], v[224:227], v[208:211], v[12:15]
	v_mfma_f32_16x16x32_bf16 v[8:11], v[232:235], v[208:211], v[8:11]
	v_mfma_f32_16x16x32_bf16 v[4:7], v[224:227], v[216:219], v[4:7]
	v_mfma_f32_16x16x32_bf16 v[0:3], v[232:235], v[216:219], v[0:3]
	v_mfma_f32_16x16x32_bf16 v[28:31], v[228:231], v[196:199], v[28:31]
	v_mfma_f32_16x16x32_bf16 v[24:27], v[236:239], v[196:199], v[24:27]
	v_mfma_f32_16x16x32_bf16 v[20:23], v[228:231], v[204:207], v[20:23]
	v_mfma_f32_16x16x32_bf16 v[16:19], v[236:239], v[204:207], v[16:19]
	v_mfma_f32_16x16x32_bf16 v[12:15], v[228:231], v[212:215], v[12:15]
	v_mfma_f32_16x16x32_bf16 v[8:11], v[236:239], v[212:215], v[8:11]
	v_mfma_f32_16x16x32_bf16 v[4:7], v[228:231], v[220:223], v[4:7]
	v_mfma_f32_16x16x32_bf16 v[0:3], v[236:239], v[220:223], v[0:3]
	s_setprio 0
	s_add_i32 s0, s0, 2
	v_lshl_add_u64 v[134:135], v[134:135], 0, s[24:25]
	v_lshl_add_u64 v[136:137], v[136:137], 0, s[24:25]
	v_lshl_add_u64 v[138:139], v[138:139], 0, s[24:25]
	s_cmp_lt_u32 s0, 12
	v_lshl_add_u64 v[140:141], v[140:141], 0, s[24:25]
	s_barrier
	s_cbranch_scc1 .LBB0_202
	v_readfirstlane_b32 s0, v169
	v_lshl_add_u64 v[130:131], v[130:131], 0, s[40:41]
	s_mov_b32 m0, s0
	v_readfirstlane_b32 s0, v168
	ds_read_b128 v[134:137], v170
	ds_read_b128 v[138:141], v170 offset:1024
	ds_read_b128 v[158:161], v170 offset:2048
	ds_read_b128 v[162:165], v170 offset:3072
	ds_read_b128 v[170:173], v152
	ds_read_b128 v[174:177], v152 offset:1024
	ds_read_b128 v[178:181], v151
	ds_read_b128 v[184:187], v151 offset:1024
	ds_read_b128 v[188:191], v150
	ds_read_b128 v[192:195], v150 offset:1024
	ds_read_b128 v[196:199], v148
	ds_read_b128 v[200:203], v148 offset:1024
	global_load_lds_dwordx4 v[130:131], off
	v_lshl_add_u64 v[130:131], v[132:133], 0, s[40:41]
	s_mov_b32 m0, s0
	s_nop 0
	global_load_lds_dwordx4 v[130:131], off
	s_barrier
	s_waitcnt lgkmcnt(0)
	s_setprio 1
	s_waitcnt lgkmcnt(0)
	v_mfma_f32_16x16x32_bf16 v[124:127], v[134:137], v[170:173], v[124:127]
	v_mfma_f32_16x16x32_bf16 v[120:123], v[158:161], v[170:173], v[120:123]
	v_mfma_f32_16x16x32_bf16 v[116:119], v[134:137], v[178:181], v[116:119]
	v_mfma_f32_16x16x32_bf16 v[112:115], v[158:161], v[178:181], v[112:115]
	v_mfma_f32_16x16x32_bf16 v[100:103], v[134:137], v[196:199], v[100:103]
	v_mfma_f32_16x16x32_bf16 v[96:99], v[158:161], v[196:199], v[96:99]
	v_mfma_f32_16x16x32_bf16 v[124:127], v[138:141], v[174:177], v[124:127]
	v_mfma_f32_16x16x32_bf16 v[120:123], v[162:165], v[174:177], v[120:123]
	v_mfma_f32_16x16x32_bf16 v[116:119], v[138:141], v[184:187], v[116:119]
	v_mfma_f32_16x16x32_bf16 v[112:115], v[162:165], v[184:187], v[112:115]
	v_mfma_f32_16x16x32_bf16 v[108:111], v[134:137], v[188:191], v[108:111]
	v_mfma_f32_16x16x32_bf16 v[104:107], v[158:161], v[188:191], v[104:107]
	v_mfma_f32_16x16x32_bf16 v[100:103], v[138:141], v[200:203], v[100:103]
	v_mfma_f32_16x16x32_bf16 v[96:99], v[162:165], v[200:203], v[96:99]
	v_mfma_f32_16x16x32_bf16 v[130:133], v[138:141], v[192:195], v[108:111]
	v_mfma_f32_16x16x32_bf16 v[204:207], v[162:165], v[192:195], v[104:107]
	s_setprio 0
	s_barrier
	s_nop 0
	ds_read_b128 v[104:107], v166
	ds_read_b128 v[108:111], v166 offset:1024
	ds_read_b128 v[208:211], v166 offset:2048
	ds_read_b128 v[166:169], v166 offset:3072
	s_barrier
	s_waitcnt lgkmcnt(0)
	s_setprio 1
	s_waitcnt lgkmcnt(3)
	v_mfma_f32_16x16x32_bf16 v[84:87], v[104:107], v[178:181], v[84:87]
	s_waitcnt lgkmcnt(1)
	v_mfma_f32_16x16x32_bf16 v[80:83], v[208:211], v[178:181], v[80:83]
	v_mfma_f32_16x16x32_bf16 v[68:71], v[104:107], v[196:199], v[68:71]
	v_mfma_f32_16x16x32_bf16 v[64:67], v[208:211], v[196:199], v[64:67]
	v_mfma_f32_16x16x32_bf16 v[92:95], v[104:107], v[170:173], v[92:95]
	v_mfma_f32_16x16x32_bf16 v[88:91], v[208:211], v[170:173], v[88:91]
	v_mfma_f32_16x16x32_bf16 v[84:87], v[108:111], v[184:187], v[84:87]
	s_waitcnt lgkmcnt(0)
	v_mfma_f32_16x16x32_bf16 v[80:83], v[166:169], v[184:187], v[80:83]
	v_mfma_f32_16x16x32_bf16 v[76:79], v[104:107], v[188:191], v[76:79]
	v_mfma_f32_16x16x32_bf16 v[72:75], v[208:211], v[188:191], v[72:75]
	v_mfma_f32_16x16x32_bf16 v[68:71], v[108:111], v[200:203], v[68:71]
	v_mfma_f32_16x16x32_bf16 v[64:67], v[166:169], v[200:203], v[64:67]
	v_mfma_f32_16x16x32_bf16 v[212:215], v[108:111], v[174:177], v[92:95]
	v_mfma_f32_16x16x32_bf16 v[170:173], v[166:169], v[174:177], v[88:91]
	v_mfma_f32_16x16x32_bf16 v[174:177], v[108:111], v[192:195], v[76:79]
	v_mfma_f32_16x16x32_bf16 v[178:181], v[166:169], v[192:195], v[72:75]
	s_setprio 0
	s_barrier
	s_nop 0
	ds_read_b128 v[72:75], v152 offset:16384
	ds_read_b128 v[76:79], v152 offset:17408
	ds_read_b128 v[88:91], v151 offset:16384
	ds_read_b128 v[92:95], v151 offset:17408
	ds_read_b128 v[184:187], v150 offset:16384
	ds_read_b128 v[188:191], v150 offset:17408
	ds_read_b128 v[192:195], v148 offset:16384
	ds_read_b128 v[196:199], v148 offset:17408
	s_waitcnt vmcnt(4)
	s_barrier
; #define LDA(dst, b, h) _Pragma("unroll") for (int m = 0; m < 4; ++m) _Pragma("unroll") for (int k = 0; k < 2; ++k) \
;     dst[m][k] = *reinterpret_cast<const bf16x8*>((const char*)SA(b, h) + lds_byte8(wr * 64 + m * 16 + fr, k * 32 + fq * 8))
; #define LDB(dst, b, h) _Pragma("unroll") for (int n = 0; n < 2; ++n) _Pragma("unroll") for (int k = 0; k < 2; ++k) \
;     dst[n][k] = *reinterpret_cast<const bf16x8*>((const char*)SB(b, h) + lds_byte8(wc * 32 + n * 16 + fr, k * 32 + fq * 8))
; #define MMA(ai, bj, At_, Bt_) do { __builtin_amdgcn_s_setprio(1); \
;     _Pragma("unroll") for (int m = 0; m < 4; ++m) _Pragma("unroll") for (int n = 0; n < 2; ++n) _Pragma("unroll") for (int k = 0; k < 2; ++k) \
;       acc[ai][bj][m][n] = MFMA16(Bt_[n][k], At_[m][k], acc[ai][bj][m][n]); \
;     __builtin_amdgcn_s_setprio(0); } while (0)
; #define WAIT_V(n) asm volatile("s_waitcnt vmcnt(" #n ")" ::: "memory")
; #define WAIT_L(n) asm volatile("s_waitcnt lgkmcnt(" #n ")" ::: "memory")
; #define BAR __builtin_amdgcn_s_barrier()
; template <class FL, class FS>
; DI void gemm8_tile(char* shmc, const bf16_t* __restrict__ A, const bf16_t* __restrict__ Bt, const int K, const int brow, const int bcol, FL fl, FS fs) {
;     ...
;     LDA(At, 0, 1); WAIT_V(4); BAR; WAIT_L(0); MMA(1, 0, At, B0); MMA(1, 1, At, B1); BAR; }
;   { LDB(B0, 1, 0); LDA(At, 1, 0); WAIT_V(2); BAR; WAIT_L(0); MMA(0, 0, At, B0); BAR;
;     LDB(B1, 1, 1); WAIT_V(0); BAR; WAIT_L(0); MMA(0, 1, At, B1); BAR;
;     LDA(At, 1, 1); BAR; WAIT_L(0); MMA(1, 0, At, B0); MMA(1, 1, At, B1); BAR; }
	s_waitcnt lgkmcnt(0)
	s_setprio 1
	s_waitcnt lgkmcnt(7)
	v_mfma_f32_16x16x32_bf16 v[60:63], v[134:137], v[72:75], v[60:63]
	v_mfma_f32_16x16x32_bf16 v[56:59], v[158:161], v[72:75], v[56:59]
	s_waitcnt lgkmcnt(5)
	v_mfma_f32_16x16x32_bf16 v[52:55], v[134:137], v[88:91], v[52:55]
	v_mfma_f32_16x16x32_bf16 v[48:51], v[158:161], v[88:91], v[48:51]
	s_waitcnt lgkmcnt(1)
	v_mfma_f32_16x16x32_bf16 v[36:39], v[134:137], v[192:195], v[36:39]
	v_mfma_f32_16x16x32_bf16 v[32:35], v[158:161], v[192:195], v[32:35]
	v_mfma_f32_16x16x32_bf16 v[60:63], v[138:141], v[76:79], v[60:63]
	v_mfma_f32_16x16x32_bf16 v[56:59], v[162:165], v[76:79], v[56:59]
	v_mfma_f32_16x16x32_bf16 v[52:55], v[138:141], v[92:95], v[52:55]
	v_mfma_f32_16x16x32_bf16 v[48:51], v[162:165], v[92:95], v[48:51]
	v_mfma_f32_16x16x32_bf16 v[44:47], v[134:137], v[184:187], v[44:47]
	v_mfma_f32_16x16x32_bf16 v[40:43], v[158:161], v[184:187], v[40:43]
	s_waitcnt lgkmcnt(0)
	v_mfma_f32_16x16x32_bf16 v[36:39], v[138:141], v[196:199], v[36:39]
	v_mfma_f32_16x16x32_bf16 v[32:35], v[162:165], v[196:199], v[32:35]
	v_mfma_f32_16x16x32_bf16 v[200:203], v[138:141], v[188:191], v[44:47]
	v_mfma_f32_16x16x32_bf16 v[216:219], v[162:165], v[188:191], v[40:43]
	s_setprio 0
	s_setprio 1
	v_mfma_f32_16x16x32_bf16 v[20:23], v[104:107], v[88:91], v[20:23]
	v_mfma_f32_16x16x32_bf16 v[16:19], v[208:211], v[88:91], v[16:19]
	v_mfma_f32_16x16x32_bf16 v[4:7], v[104:107], v[192:195], v[4:7]
	v_mfma_f32_16x16x32_bf16 v[0:3], v[208:211], v[192:195], v[0:3]
	v_mfma_f32_16x16x32_bf16 v[28:31], v[104:107], v[72:75], v[28:31]
	v_mfma_f32_16x16x32_bf16 v[24:27], v[208:211], v[72:75], v[24:27]
	v_mfma_f32_16x16x32_bf16 v[20:23], v[108:111], v[92:95], v[20:23]
	v_mfma_f32_16x16x32_bf16 v[16:19], v[166:169], v[92:95], v[16:19]
	v_mfma_f32_16x16x32_bf16 v[12:15], v[104:107], v[184:187], v[12:15]
	v_mfma_f32_16x16x32_bf16 v[8:11], v[208:211], v[184:187], v[8:11]
	v_mfma_f32_16x16x32_bf16 v[4:7], v[108:111], v[196:199], v[4:7]
	v_mfma_f32_16x16x32_bf16 v[0:3], v[166:169], v[196:199], v[0:3]
	v_mfma_f32_16x16x32_bf16 v[134:137], v[108:111], v[76:79], v[28:31]
	v_mfma_f32_16x16x32_bf16 v[138:141], v[166:169], v[76:79], v[24:27]
	v_mfma_f32_16x16x32_bf16 v[158:161], v[108:111], v[188:191], v[12:15]
	v_mfma_f32_16x16x32_bf16 v[162:165], v[166:169], v[188:191], v[8:11]
	s_setprio 0
	s_barrier
	s_nop 0
	ds_read_b128 v[8:11], v156
	ds_read_b128 v[12:15], v156 offset:1024
	ds_read_b128 v[166:169], v156 offset:2048
	ds_read_b128 v[184:187], v156 offset:3072
	ds_read_b128 v[24:27], v152 offset:32768
	ds_read_b128 v[28:31], v152 offset:33792
	ds_read_b128 v[40:43], v151 offset:32768
	ds_read_b128 v[44:47], v151 offset:33792
	ds_read_b128 v[188:191], v150 offset:32768
	ds_read_b128 v[192:195], v150 offset:33792
	ds_read_b128 v[196:199], v148 offset:32768
	ds_read_b128 v[208:211], v148 offset:33792
	s_waitcnt vmcnt(2)
	s_barrier
	s_waitcnt lgkmcnt(0)
	s_setprio 1
	s_waitcnt lgkmcnt(7)
	v_mfma_f32_16x16x32_bf16 v[72:75], v[8:11], v[24:27], v[124:127]
	s_waitcnt lgkmcnt(6)
	v_mfma_f32_16x16x32_bf16 v[124:127], v[12:15], v[28:31], v[72:75]
	v_mfma_f32_16x16x32_bf16 v[72:75], v[166:169], v[24:27], v[120:123]
	v_mfma_f32_16x16x32_bf16 v[120:123], v[184:187], v[28:31], v[72:75]
	s_waitcnt lgkmcnt(5)
	v_mfma_f32_16x16x32_bf16 v[72:75], v[8:11], v[40:43], v[116:119]
	s_waitcnt lgkmcnt(4)
	v_mfma_f32_16x16x32_bf16 v[108:111], v[12:15], v[44:47], v[72:75]
	v_mfma_f32_16x16x32_bf16 v[72:75], v[166:169], v[40:43], v[112:115]
	v_mfma_f32_16x16x32_bf16 v[104:107], v[184:187], v[44:47], v[72:75]
	s_waitcnt lgkmcnt(3)
	v_mfma_f32_16x16x32_bf16 v[72:75], v[8:11], v[188:191], v[130:133]
	s_waitcnt lgkmcnt(2)
	v_mfma_f32_16x16x32_bf16 v[92:95], v[12:15], v[192:195], v[72:75]
	v_mfma_f32_16x16x32_bf16 v[72:75], v[166:169], v[188:191], v[204:207]
	v_mfma_f32_16x16x32_bf16 v[88:91], v[184:187], v[192:195], v[72:75]
	s_waitcnt lgkmcnt(1)
	v_mfma_f32_16x16x32_bf16 v[72:75], v[8:11], v[196:199], v[100:103]
	s_waitcnt lgkmcnt(0)
	v_mfma_f32_16x16x32_bf16 v[76:79], v[12:15], v[208:211], v[72:75]
	v_mfma_f32_16x16x32_bf16 v[72:75], v[166:169], v[196:199], v[96:99]
	v_mfma_f32_16x16x32_bf16 v[72:75], v[184:187], v[208:211], v[72:75]
	s_setprio 0
	s_barrier
	ds_read_b128 v[130:133], v154
	ds_read_b128 v[204:207], v154 offset:1024
	ds_read_b128 v[220:223], v154 offset:2048
	ds_read_b128 v[154:157], v154 offset:3072
	s_waitcnt vmcnt(0)
	s_barrier
	s_waitcnt lgkmcnt(0)
	s_setprio 1
	s_waitcnt lgkmcnt(3)
	v_mfma_f32_16x16x32_bf16 v[96:99], v[130:133], v[24:27], v[212:215]
	s_waitcnt lgkmcnt(1)
	v_mfma_f32_16x16x32_bf16 v[24:27], v[220:223], v[24:27], v[170:173]
	s_waitcnt lgkmcnt(0)
	v_mfma_f32_16x16x32_bf16 v[112:115], v[154:157], v[28:31], v[24:27]
	v_mfma_f32_16x16x32_bf16 v[24:27], v[130:133], v[40:43], v[84:87]
	v_mfma_f32_16x16x32_bf16 v[100:103], v[204:207], v[44:47], v[24:27]
	v_mfma_f32_16x16x32_bf16 v[24:27], v[220:223], v[40:43], v[80:83]
	v_mfma_f32_16x16x32_bf16 v[116:119], v[204:207], v[28:31], v[96:99]
	v_mfma_f32_16x16x32_bf16 v[96:99], v[154:157], v[44:47], v[24:27]
	v_mfma_f32_16x16x32_bf16 v[24:27], v[130:133], v[188:191], v[174:177]
	v_mfma_f32_16x16x32_bf16 v[84:87], v[204:207], v[192:195], v[24:27]
	v_mfma_f32_16x16x32_bf16 v[24:27], v[220:223], v[188:191], v[178:181]
	v_mfma_f32_16x16x32_bf16 v[80:83], v[154:157], v[192:195], v[24:27]
	v_mfma_f32_16x16x32_bf16 v[24:27], v[130:133], v[196:199], v[68:71]
	v_mfma_f32_16x16x32_bf16 v[68:71], v[204:207], v[208:211], v[24:27]
	v_mfma_f32_16x16x32_bf16 v[24:27], v[220:223], v[196:199], v[64:67]
	v_mfma_f32_16x16x32_bf16 v[64:67], v[154:157], v[208:211], v[24:27]
	s_setprio 0
	s_barrier
; #define LDA(dst, b, h) _Pragma("unroll") for (int m = 0; m < 4; ++m) _Pragma("unroll") for (int k = 0; k < 2; ++k) \
;     dst[m][k] = *reinterpret_cast<const bf16x8*>((const char*)SA(b, h) + lds_byte8(wr * 64 + m * 16 + fr, k * 32 + fq * 8))
; #define MMA(ai, bj, At_, Bt_) do { __builtin_amdgcn_s_setprio(1); \
;     _Pragma("unroll") for (int m = 0; m < 4; ++m) _Pragma("unroll") for (int n = 0; n < 2; ++n) _Pragma("unroll") for (int k = 0; k < 2; ++k) \
;       acc[ai][bj][m][n] = MFMA16(Bt_[n][k], At_[m][k], acc[ai][bj][m][n]); \
;     __builtin_amdgcn_s_setprio(0); } while (0)
; #define WAIT_L(n) asm volatile("s_waitcnt lgkmcnt(" #n ")" ::: "memory")
; #define BAR __builtin_amdgcn_s_barrier()
; DI void st_bf4(bf16_t* p, float a, float b, float c, float d) { uint2 v; v.x = pack2(a, b); v.y = pack2(c, d); *(uint2*)p = v; }
; template <class FL, class FS>
; DI void gemm8_tile(char* shmc, const bf16_t* __restrict__ A, const bf16_t* __restrict__ Bt, const int K, const int brow, const int bcol, FL fl, FS fs) {
;     ...
;     LDA(At, 1, 1); BAR; WAIT_L(0); MMA(1, 0, At, B0); MMA(1, 1, At, B1); BAR; }
;   if (wr == 0) BAR;
; #pragma unroll
;   for (int ai = 0; ai < 2; ++ai)
; #pragma unroll
;     for (int mh = 0; mh < 2; ++mh) {
;       decltype(fl(0, 0)) ld[2][2][2];
; #pragma unroll
;       for (int mm = 0; mm < 2; ++mm)
; #pragma unroll
;         for (int bj = 0; bj < 2; ++bj)
; #pragma unroll
;           for (int n = 0; n < 2; ++n) ld[mm][bj][n] = fl(brow + ai * HALF + wr * 64 + (2 * mh + mm) * 16 + fr, bcol + bj * HALF + wc * 32 + n * 16 + 4 * fq);
; #pragma unroll
;       for (int mm = 0; mm < 2; ++mm)
; #pragma unroll
;         for (int bj = 0; bj < 2; ++bj)
; #pragma unroll
;           for (int n = 0; n < 2; ++n) fs(brow + ai * HALF + wr * 64 + (2 * mh + mm) * 16 + fr, bcol + bj * HALF + wc * 32 + n * 16 + 4 * fq, acc[ai][bj][2 * mh + mm][n], ld[mm][bj][n]);
; DI void phase_g1(const Params& p, const Sub& s, char* lds_all) {
;     ...
;       [&](int row, int col, f32x4 v, const NoLoad&) {
;         if (col < 1024) {
;           if (row < MP) st_bf4(ugm + ((size_t)(col >> 4) * MP + row) * 16 + (col & 15), v[0], v[1], v[2], v[3]);
;           else *(f32x4*)(us + (size_t)(row - MP) * D + col) = v;
;         } else st_bf4(z + (size_t)row * D + (col - 1024), v[0], v[1], v[2], v[3]);
;       });
	ds_read_b128 v[170:173], v152 offset:49152
	ds_read_b128 v[174:177], v152 offset:50176
	ds_read_b128 v[178:181], v151 offset:49152
	ds_read_b128 v[188:191], v151 offset:50176
	ds_read_b128 v[192:195], v150 offset:49152
	ds_read_b128 v[150:153], v150 offset:50176
	ds_read_b128 v[196:199], v148 offset:49152
	ds_read_b128 v[208:211], v148 offset:50176
	s_barrier
	s_waitcnt lgkmcnt(0)
	s_setprio 1
	s_waitcnt lgkmcnt(7)
	v_mfma_f32_16x16x32_bf16 v[24:27], v[8:11], v[170:173], v[60:63]
	s_waitcnt lgkmcnt(6)
	v_mfma_f32_16x16x32_bf16 v[60:63], v[12:15], v[174:177], v[24:27]
	v_mfma_f32_16x16x32_bf16 v[24:27], v[166:169], v[170:173], v[56:59]
	v_mfma_f32_16x16x32_bf16 v[56:59], v[184:187], v[174:177], v[24:27]
	s_waitcnt lgkmcnt(5)
	v_mfma_f32_16x16x32_bf16 v[24:27], v[8:11], v[178:181], v[52:55]
	s_waitcnt lgkmcnt(4)
	v_mfma_f32_16x16x32_bf16 v[44:47], v[12:15], v[188:191], v[24:27]
	v_mfma_f32_16x16x32_bf16 v[24:27], v[166:169], v[178:181], v[48:51]
	v_mfma_f32_16x16x32_bf16 v[40:43], v[184:187], v[188:191], v[24:27]
	s_waitcnt lgkmcnt(3)
	v_mfma_f32_16x16x32_bf16 v[24:27], v[8:11], v[192:195], v[200:203]
	s_waitcnt lgkmcnt(1)
	v_mfma_f32_16x16x32_bf16 v[8:11], v[8:11], v[196:199], v[36:39]
	v_mfma_f32_16x16x32_bf16 v[28:31], v[12:15], v[150:153], v[24:27]
	v_mfma_f32_16x16x32_bf16 v[24:27], v[166:169], v[192:195], v[216:219]
	s_waitcnt lgkmcnt(0)
	v_mfma_f32_16x16x32_bf16 v[12:15], v[12:15], v[208:211], v[8:11]
	v_mfma_f32_16x16x32_bf16 v[8:11], v[166:169], v[196:199], v[32:35]
	v_mfma_f32_16x16x32_bf16 v[24:27], v[184:187], v[150:153], v[24:27]
	v_mfma_f32_16x16x32_bf16 v[8:11], v[184:187], v[208:211], v[8:11]
	s_setprio 0
	s_setprio 1
	v_mfma_f32_16x16x32_bf16 v[32:35], v[130:133], v[170:173], v[134:137]
	v_mfma_f32_16x16x32_bf16 v[52:55], v[204:207], v[174:177], v[32:35]
	v_mfma_f32_16x16x32_bf16 v[32:35], v[220:223], v[170:173], v[138:141]
	v_mfma_f32_16x16x32_bf16 v[16:19], v[220:223], v[178:181], v[16:19]
	v_mfma_f32_16x16x32_bf16 v[48:51], v[154:157], v[174:177], v[32:35]
	v_mfma_f32_16x16x32_bf16 v[20:23], v[130:133], v[178:181], v[20:23]
	v_mfma_f32_16x16x32_bf16 v[32:35], v[154:157], v[188:191], v[16:19]
	v_mfma_f32_16x16x32_bf16 v[16:19], v[130:133], v[192:195], v[158:161]
	v_mfma_f32_16x16x32_bf16 v[36:39], v[204:207], v[188:191], v[20:23]
	v_mfma_f32_16x16x32_bf16 v[20:23], v[204:207], v[150:153], v[16:19]
	v_mfma_f32_16x16x32_bf16 v[16:19], v[220:223], v[192:195], v[162:165]
	v_mfma_f32_16x16x32_bf16 v[4:7], v[130:133], v[196:199], v[4:7]
	v_mfma_f32_16x16x32_bf16 v[0:3], v[220:223], v[196:199], v[0:3]
	v_mfma_f32_16x16x32_bf16 v[16:19], v[154:157], v[150:153], v[16:19]
	v_mfma_f32_16x16x32_bf16 v[4:7], v[204:207], v[208:211], v[4:7]
	v_mfma_f32_16x16x32_bf16 v[0:3], v[154:157], v[208:211], v[0:3]
	s_setprio 0
	v_cmp_gt_u32_e32 vcc, s48, v128
	s_barrier
	s_and_saveexec_b64 s[0:1], vcc
	s_cbranch_execz .LBB0_205
	s_barrier
.LBB0_205:
	s_or_b64 exec, exec, s[0:1]
	s_mov_b32 s99, s6
	s_mov_b32 s100, s4
	s_mov_b32 s98, 1
	v_readlane_b32 s0, v251, 1
	s_add_i32 s51, s51, s0
	s_cmpk_lt_i32 s51, 0x800
	s_cbranch_scc1 .LBB0_199
	s_mov_b32 s101, 1
.Lg1_epi:
	v_and_b32_e32 v226, 15, v182
	v_bfe_u32 v227, v182, 4, 2
	v_bfe_u32 v228, v182, 6, 2
	v_lshrrev_b32_e32 v229, 8, v182
	v_lshl_add_u32 v230, v229, 6, v226
	v_and_b32_e32 v231, 1, v227
	v_lshrrev_b32_e32 v232, 1, v227
	s_cmp_lt_u32 s100, 0x400
	s_cbranch_scc0 .Lg1_epi_z
	v_lshl_add_u32 v233, v228, 1, v231
	v_lshlrev_b32_e32 v233, 21, v233
	v_lshl_add_u32 v233, v230, 5, v233
	v_lshl_add_u32 v233, v232, 4, v233
	s_lshl_b32 s0, s100, 17
	s_lshl_b32 s1, s99, 5
	s_add_u32 s0, s0, s1
	s_add_u32 s0, s16, s0
	s_addc_u32 s1, s17, 0
	s_add_u32 s2, s0, 0x1000000
	s_addc_u32 s3, s1, 0
	s_add_u32 s8, s0, 0x1000
	s_addc_u32 s9, s1, 0
	s_add_u32 s10, s2, 0x1000
	s_addc_u32 s11, s3, 0
	v_cvt_pk_bf16_f32 v124, v124, v125
	v_cvt_pk_bf16_f32 v125, v126, v127
	v_cvt_pk_bf16_f32 v126, v120, v121
	v_cvt_pk_bf16_f32 v127, v122, v123
	v_cvt_pk_bf16_f32 v108, v108, v109
	v_cvt_pk_bf16_f32 v109, v110, v111
	v_cvt_pk_bf16_f32 v110, v104, v105
	v_cvt_pk_bf16_f32 v111, v106, v107
	v_permlane16_swap_b32_e32 v124, v126
	v_permlane16_swap_b32_e32 v125, v127
	global_store_dwordx4 v233, v[124:127], s[0:1]
	v_cvt_pk_bf16_f32 v92, v92, v93
	v_cvt_pk_bf16_f32 v93, v94, v95
	v_cvt_pk_bf16_f32 v94, v88, v89
	v_cvt_pk_bf16_f32 v95, v90, v91
	v_permlane16_swap_b32_e32 v108, v110
	v_permlane16_swap_b32_e32 v109, v111
	global_store_dwordx4 v233, v[108:111], s[0:1] offset:512
	v_cvt_pk_bf16_f32 v76, v76, v77
	v_cvt_pk_bf16_f32 v77, v78, v79
	v_cvt_pk_bf16_f32 v78, v72, v73
	v_cvt_pk_bf16_f32 v79, v74, v75
	v_permlane16_swap_b32_e32 v92, v94
	v_permlane16_swap_b32_e32 v93, v95
	global_store_dwordx4 v233, v[92:95], s[0:1] offset:1024
	v_cvt_pk_bf16_f32 v116, v116, v117
	v_cvt_pk_bf16_f32 v117, v118, v119
	v_cvt_pk_bf16_f32 v118, v112, v113
	v_cvt_pk_bf16_f32 v119, v114, v115
	v_permlane16_swap_b32_e32 v76, v78
	v_permlane16_swap_b32_e32 v77, v79
	global_store_dwordx4 v233, v[76:79], s[0:1] offset:1536
	v_cvt_pk_bf16_f32 v100, v100, v101
	v_cvt_pk_bf16_f32 v101, v102, v103
	v_cvt_pk_bf16_f32 v102, v96, v97
	v_cvt_pk_bf16_f32 v103, v98, v99
	v_permlane16_swap_b32_e32 v116, v118
	v_permlane16_swap_b32_e32 v117, v119
	global_store_dwordx4 v233, v[116:119], s[2:3]
	v_cvt_pk_bf16_f32 v84, v84, v85
	v_cvt_pk_bf16_f32 v85, v86, v87
	v_cvt_pk_bf16_f32 v86, v80, v81
	v_cvt_pk_bf16_f32 v87, v82, v83
	v_permlane16_swap_b32_e32 v100, v102
	v_permlane16_swap_b32_e32 v101, v103
	global_store_dwordx4 v233, v[100:103], s[2:3] offset:512
	v_cvt_pk_bf16_f32 v68, v68, v69
	v_cvt_pk_bf16_f32 v69, v70, v71
	v_cvt_pk_bf16_f32 v70, v64, v65
; DI void st_bf4(bf16_t* p, float a, float b, float c, float d) { uint2 v; v.x = pack2(a, b); v.y = pack2(c, d); *(uint2*)p = v; }
; DI void phase_g1(const Params& p, const Sub& s, char* lds_all) {
;     ...
;       [&](int row, int col, f32x4 v, const NoLoad&) {
;         if (col < 1024) {
;           if (row < MP) st_bf4(ugm + ((size_t)(col >> 4) * MP + row) * 16 + (col & 15), v[0], v[1], v[2], v[3]);
;           else *(f32x4*)(us + (size_t)(row - MP) * D + col) = v;
	v_cvt_pk_bf16_f32 v71, v66, v67
	v_permlane16_swap_b32_e32 v84, v86
	v_permlane16_swap_b32_e32 v85, v87
	global_store_dwordx4 v233, v[84:87], s[2:3] offset:1024
	v_cvt_pk_bf16_f32 v60, v60, v61
	v_cvt_pk_bf16_f32 v61, v62, v63
	v_cvt_pk_bf16_f32 v62, v56, v57
	v_cvt_pk_bf16_f32 v63, v58, v59
	v_permlane16_swap_b32_e32 v68, v70
	v_permlane16_swap_b32_e32 v69, v71
	global_store_dwordx4 v233, v[68:71], s[2:3] offset:1536
	v_cvt_pk_bf16_f32 v44, v44, v45
	v_cvt_pk_bf16_f32 v45, v46, v47
	v_cvt_pk_bf16_f32 v46, v40, v41
	v_cvt_pk_bf16_f32 v47, v42, v43
	v_permlane16_swap_b32_e32 v60, v62
	v_permlane16_swap_b32_e32 v61, v63
	global_store_dwordx4 v233, v[60:63], s[8:9]
	v_cvt_pk_bf16_f32 v28, v28, v29
	v_cvt_pk_bf16_f32 v29, v30, v31
	v_cvt_pk_bf16_f32 v30, v24, v25
	v_cvt_pk_bf16_f32 v31, v26, v27
	v_permlane16_swap_b32_e32 v44, v46
	v_permlane16_swap_b32_e32 v45, v47
	global_store_dwordx4 v233, v[44:47], s[8:9] offset:512
	v_cvt_pk_bf16_f32 v12, v12, v13
	v_cvt_pk_bf16_f32 v13, v14, v15
	v_cvt_pk_bf16_f32 v14, v8, v9
	v_cvt_pk_bf16_f32 v15, v10, v11
	v_permlane16_swap_b32_e32 v28, v30
	v_permlane16_swap_b32_e32 v29, v31
	global_store_dwordx4 v233, v[28:31], s[8:9] offset:1024
	v_cvt_pk_bf16_f32 v52, v52, v53
	v_cvt_pk_bf16_f32 v53, v54, v55
	v_cvt_pk_bf16_f32 v54, v48, v49
	v_cvt_pk_bf16_f32 v55, v50, v51
	v_permlane16_swap_b32_e32 v12, v14
	v_permlane16_swap_b32_e32 v13, v15
	global_store_dwordx4 v233, v[12:15], s[8:9] offset:1536
	v_cvt_pk_bf16_f32 v36, v36, v37
	v_cvt_pk_bf16_f32 v37, v38, v39
	v_cvt_pk_bf16_f32 v38, v32, v33
	v_cvt_pk_bf16_f32 v39, v34, v35
	v_permlane16_swap_b32_e32 v52, v54
	v_permlane16_swap_b32_e32 v53, v55
	global_store_dwordx4 v233, v[52:55], s[10:11]
	v_cvt_pk_bf16_f32 v20, v20, v21
	v_cvt_pk_bf16_f32 v21, v22, v23
	v_cvt_pk_bf16_f32 v22, v16, v17
	v_cvt_pk_bf16_f32 v23, v18, v19
	v_permlane16_swap_b32_e32 v36, v38
	v_permlane16_swap_b32_e32 v37, v39
	global_store_dwordx4 v233, v[36:39], s[10:11] offset:512
	v_cvt_pk_bf16_f32 v4, v4, v5
	v_cvt_pk_bf16_f32 v5, v6, v7
	v_cvt_pk_bf16_f32 v6, v0, v1
	v_cvt_pk_bf16_f32 v7, v2, v3
	v_permlane16_swap_b32_e32 v20, v22
	v_permlane16_swap_b32_e32 v21, v23
	global_store_dwordx4 v233, v[20:23], s[10:11] offset:1024
	v_permlane16_swap_b32_e32 v4, v6
	v_permlane16_swap_b32_e32 v5, v7
	global_store_dwordx4 v233, v[4:7], s[10:11] offset:1536
	s_branch .Lg1_epi_done
; DI void st_bf4(bf16_t* p, float a, float b, float c, float d) { uint2 v; v.x = pack2(a, b); v.y = pack2(c, d); *(uint2*)p = v; }
; DI void phase_g1(const Params& p, const Sub& s, char* lds_all) {
;     ...
;       [&](int row, int col, f32x4 v, const NoLoad&) {
;         if (col < 1024) {
;           if (row < MP) st_bf4(ugm + ((size_t)(col >> 4) * MP + row) * 16 + (col & 15), v[0], v[1], v[2], v[3]);
;           else *(f32x4*)(us + (size_t)(row - MP) * D + col) = v;
;         } else st_bf4(z + (size_t)row * D + (col - 1024), v[0], v[1], v[2], v[3]);
;       });
.Lg1_epi_z:
	v_lshlrev_b32_e32 v233, 11, v230
	v_lshl_add_u32 v233, v228, 6, v233
	v_lshl_add_u32 v233, v231, 5, v233
	v_lshl_add_u32 v233, v232, 4, v233
	s_lshl_b32 s0, s99, 11
	s_add_u32 s0, s18, s0
	s_addc_u32 s1, s19, 0
	s_sub_u32 s2, s100, 0x400
	s_lshl_b32 s2, s2, 1
	s_add_u32 s0, s0, s2
	s_addc_u32 s1, s1, 0
	v_cvt_pk_bf16_f32 v124, v124, v125
	v_cvt_pk_bf16_f32 v125, v126, v127
	v_cvt_pk_bf16_f32 v126, v120, v121
	v_cvt_pk_bf16_f32 v127, v122, v123
	v_cvt_pk_bf16_f32 v116, v116, v117
	v_cvt_pk_bf16_f32 v117, v118, v119
	v_cvt_pk_bf16_f32 v118, v112, v113
	v_cvt_pk_bf16_f32 v119, v114, v115
	v_permlane16_swap_b32_e32 v124, v126
	v_permlane16_swap_b32_e32 v125, v127
	global_store_dwordx4 v233, v[124:127], s[0:1]
	v_cvt_pk_bf16_f32 v108, v108, v109
	v_cvt_pk_bf16_f32 v109, v110, v111
	v_cvt_pk_bf16_f32 v110, v104, v105
	v_cvt_pk_bf16_f32 v111, v106, v107
	v_permlane16_swap_b32_e32 v116, v118
	v_permlane16_swap_b32_e32 v117, v119
	global_store_dwordx4 v233, v[116:119], s[0:1] offset:256
	v_cvt_pk_bf16_f32 v100, v100, v101
	v_cvt_pk_bf16_f32 v101, v102, v103
	v_cvt_pk_bf16_f32 v102, v96, v97
	v_cvt_pk_bf16_f32 v103, v98, v99
	s_add_u32 s0, s0, 0x8000
	s_addc_u32 s1, s1, 0
	v_permlane16_swap_b32_e32 v108, v110
	v_permlane16_swap_b32_e32 v109, v111
	global_store_dwordx4 v233, v[108:111], s[0:1]
	v_cvt_pk_bf16_f32 v92, v92, v93
	v_cvt_pk_bf16_f32 v93, v94, v95
	v_cvt_pk_bf16_f32 v94, v88, v89
	v_cvt_pk_bf16_f32 v95, v90, v91
	v_permlane16_swap_b32_e32 v100, v102
	v_permlane16_swap_b32_e32 v101, v103
	global_store_dwordx4 v233, v[100:103], s[0:1] offset:256
	v_cvt_pk_bf16_f32 v84, v84, v85
	v_cvt_pk_bf16_f32 v85, v86, v87
	v_cvt_pk_bf16_f32 v86, v80, v81
	v_cvt_pk_bf16_f32 v87, v82, v83
	s_add_u32 s0, s0, 0x8000
	s_addc_u32 s1, s1, 0
	v_permlane16_swap_b32_e32 v92, v94
	v_permlane16_swap_b32_e32 v93, v95
	global_store_dwordx4 v233, v[92:95], s[0:1]
	v_cvt_pk_bf16_f32 v76, v76, v77
	v_cvt_pk_bf16_f32 v77, v78, v79
	v_cvt_pk_bf16_f32 v78, v72, v73
	v_cvt_pk_bf16_f32 v79, v74, v75
	v_permlane16_swap_b32_e32 v84, v86
	v_permlane16_swap_b32_e32 v85, v87
	global_store_dwordx4 v233, v[84:87], s[0:1] offset:256
	v_cvt_pk_bf16_f32 v68, v68, v69
	v_cvt_pk_bf16_f32 v69, v70, v71
	v_cvt_pk_bf16_f32 v70, v64, v65
	v_cvt_pk_bf16_f32 v71, v66, v67
	s_add_u32 s0, s0, 0x8000
	s_addc_u32 s1, s1, 0
	v_permlane16_swap_b32_e32 v76, v78
	v_permlane16_swap_b32_e32 v77, v79
	global_store_dwordx4 v233, v[76:79], s[0:1]
	v_cvt_pk_bf16_f32 v60, v60, v61
	v_cvt_pk_bf16_f32 v61, v62, v63
	v_cvt_pk_bf16_f32 v62, v56, v57
	v_cvt_pk_bf16_f32 v63, v58, v59
	v_permlane16_swap_b32_e32 v68, v70
	v_permlane16_swap_b32_e32 v69, v71
	global_store_dwordx4 v233, v[68:71], s[0:1] offset:256
	v_cvt_pk_bf16_f32 v52, v52, v53
	v_cvt_pk_bf16_f32 v53, v54, v55
	v_cvt_pk_bf16_f32 v54, v48, v49
	v_cvt_pk_bf16_f32 v55, v50, v51
	s_add_u32 s0, s0, 0x28000
	s_addc_u32 s1, s1, 0
	v_permlane16_swap_b32_e32 v60, v62
	v_permlane16_swap_b32_e32 v61, v63
	global_store_dwordx4 v233, v[60:63], s[0:1]
	v_cvt_pk_bf16_f32 v44, v44, v45
	v_cvt_pk_bf16_f32 v45, v46, v47
	v_cvt_pk_bf16_f32 v46, v40, v41
	v_cvt_pk_bf16_f32 v47, v42, v43
	v_permlane16_swap_b32_e32 v52, v54
	v_permlane16_swap_b32_e32 v53, v55
	global_store_dwordx4 v233, v[52:55], s[0:1] offset:256
	v_cvt_pk_bf16_f32 v36, v36, v37
	v_cvt_pk_bf16_f32 v37, v38, v39
	v_cvt_pk_bf16_f32 v38, v32, v33
	v_cvt_pk_bf16_f32 v39, v34, v35
	s_add_u32 s0, s0, 0x8000
	s_addc_u32 s1, s1, 0
	v_permlane16_swap_b32_e32 v44, v46
	v_permlane16_swap_b32_e32 v45, v47
	global_store_dwordx4 v233, v[44:47], s[0:1]
	v_cvt_pk_bf16_f32 v28, v28, v29
	v_cvt_pk_bf16_f32 v29, v30, v31
	v_cvt_pk_bf16_f32 v30, v24, v25
	v_cvt_pk_bf16_f32 v31, v26, v27
	v_permlane16_swap_b32_e32 v36, v38
	v_permlane16_swap_b32_e32 v37, v39
	global_store_dwordx4 v233, v[36:39], s[0:1] offset:256
	v_cvt_pk_bf16_f32 v20, v20, v21
	v_cvt_pk_bf16_f32 v21, v22, v23
	v_cvt_pk_bf16_f32 v22, v16, v17
	v_cvt_pk_bf16_f32 v23, v18, v19
	s_add_u32 s0, s0, 0x8000
	s_addc_u32 s1, s1, 0
	v_permlane16_swap_b32_e32 v28, v30
	v_permlane16_swap_b32_e32 v29, v31
	global_store_dwordx4 v233, v[28:31], s[0:1]
	v_cvt_pk_bf16_f32 v12, v12, v13
	v_cvt_pk_bf16_f32 v13, v14, v15
	v_cvt_pk_bf16_f32 v14, v8, v9
	v_cvt_pk_bf16_f32 v15, v10, v11
	v_permlane16_swap_b32_e32 v20, v22
	v_permlane16_swap_b32_e32 v21, v23
	global_store_dwordx4 v233, v[20:23], s[0:1] offset:256
	v_cvt_pk_bf16_f32 v4, v4, v5
	v_cvt_pk_bf16_f32 v5, v6, v7
	v_cvt_pk_bf16_f32 v6, v0, v1
	v_cvt_pk_bf16_f32 v7, v2, v3
	s_add_u32 s0, s0, 0x8000
	s_addc_u32 s1, s1, 0
	v_permlane16_swap_b32_e32 v12, v14
	v_permlane16_swap_b32_e32 v13, v15
	global_store_dwordx4 v233, v[12:15], s[0:1]
	v_permlane16_swap_b32_e32 v4, v6
	v_permlane16_swap_b32_e32 v5, v7
	global_store_dwordx4 v233, v[4:7], s[0:1] offset:256
	s_branch .Lg1_epi_done
.Lg1_epi_done:
	s_cmp_eq_u32 s101, 0
	s_cbranch_scc1 .Lg1_epi_ret0
	s_branch .LBB0_460
.Lg1_w22:
	s_waitcnt vmcnt(22)
	s_branch .Lg1_wd

; #define VBID ((int)(blockIdx.x * 2 + (otid() >> 8)))
; #define LAS __attribute__((address_space(3)))
; template <class FA, class FB, class FL, class FS>
; DI void gemm_tile(char* lds, int ksteps, int rot, FA fa, FB fb, FL fl, FS fs) {
;     ...
;   for (int i = 0; i < 4; ++i) {
;     const int id = tid + i * 256, r = id >> 3, c = (id & 7) ^ (r & 7);
;     __builtin_amdgcn_global_load_lds((const unsigned*)fa(r, rot * 8 + c), (LAS unsigned*)(l3 + id * 16), 16, 0, 0);
;     __builtin_amdgcn_global_load_lds((const unsigned*)fb(r, rot * 8 + c), (LAS unsigned*)(l3 + 16384 + id * 16), 16, 0, 0);
;   }
;   asm volatile("s_waitcnt vmcnt(0)" ::: "memory");
;   __syncthreads();
; DI void phase_s5_y(const Params& p, char* lds) {
;     ...
;   const int nt = 64 * 8 * 8;
;   for (int k_ = 0; k_ * VGRID < (nt); ++k_) {
;     int L = k_ * VGRID + VBID; const bool active_ = L < (nt); if (!active_) L = (nt) - 1;
;     const int j = 3 - (L >> 10), rem = L & 1023, g = rem >> 4, mt = rem & 15;
;     const bf16_t* Ug = ugm + (size_t)g * MP * 16 + (size_t)mt * 128 * 512;
;     const bf16_t* Hg = H + ((size_t)g * 2048 + mt * 128) * 128;
;     gemm_tile(lds, 2 + 2 * (j + 1), 0,
;       [&](int r, int kc) { return kc < 16 ? Hg + (size_t)r * 128 + kc * 8 : Ug + (size_t)r * 512 + (kc - 16) * 8; },
.LBB0_625:
	v_mov_b32_e32 v0, v182
	v_readlane_b32 s1, v251, 7
	v_ashrrev_i32_e32 v0, 8, v0
	s_add_i32 s0, s0, s1
	v_add_u32_e32 v0, s0, v0
	v_min_i32_e32 v0, 0xfff, v0
	v_and_b32_e32 v70, 0x600, v0
	v_and_b32_e32 v71, 0x800, v0
	v_and_b32_e32 v0, 0x1ff, v0
	v_lshl_or_b32 v0, v70, 1, v0
	v_lshrrev_b32_e32 v71, 2, v71
	v_or_b32_e32 v0, v0, v71
	v_bfe_u32 v70, v0, 4, 6
	v_and_b32_e32 v71, 15, v0
	v_lshlrev_b32_e32 v68, 19, v70
	v_mov_b32_e32 v26, v182
	v_ashrrev_i32_e32 v154, 10, v0
	v_lshl_add_u64 v[0:1], s[8:9], 0, v[68:69]
	v_lshlrev_b32_e32 v68, 15, v71
	v_lshl_add_u64 v[6:7], v[0:1], 0, v[68:69]
	v_bfe_u32 v24, v26, 3, 5
	v_xor_b32_e32 v0, v24, v26
	v_lshlrev_b32_sdwa v82, v103, v26 dst_sel:DWORD dst_unused:UNUSED_PAD src0_sel:DWORD src1_sel:BYTE_0
	v_lshlrev_b32_e32 v68, 8, v24
	v_lshlrev_b32_e32 v0, 4, v0
	v_add_u32_e32 v56, v102, v82
	v_sub_u32_e32 v91, 3, v154
	v_lshl_add_u64 v[8:9], v[6:7], 0, v[68:69]
	v_and_b32_e32 v68, 0x70, v0
	v_readfirstlane_b32 s0, v56
	v_lshl_add_u64 v[0:1], v[8:9], 0, v[68:69]
	s_mov_b32 m0, s0
	v_lshlrev_b32_e32 v81, 7, v91
	global_load_lds_dwordx4 v[0:1], off
	v_or_b32_e32 v0, v81, v24
	v_mov_b32_e32 v1, v69
	v_lshlrev_b32_e32 v2, 17, v70
	v_mov_b32_e32 v3, v69
	v_lshl_add_u64 v[10:11], s[10:11], 0, v[2:3]
	v_lshlrev_b64 v[2:3], 8, v[0:1]
	v_add_u32_e32 v1, 0x4000, v56
	v_lshl_add_u64 v[22:23], v[10:11], 0, v[2:3]
	v_readfirstlane_b32 s0, v1
	v_or_b32_sdwa v1, v26, s33 dst_sel:DWORD dst_unused:UNUSED_PAD src0_sel:BYTE_0 src1_sel:DWORD
	v_lshl_add_u64 v[2:3], v[22:23], 0, v[68:69]
	s_mov_b32 m0, s0
	v_lshrrev_b32_e32 v155, 3, v1
	global_load_lds_dwordx4 v[2:3], off
	v_xor_b32_e32 v2, v155, v26
	v_lshlrev_b32_e32 v83, 4, v1
	v_lshlrev_b32_e32 v68, 8, v155
	v_lshlrev_b32_e32 v2, 4, v2
	v_add_u32_e32 v1, v102, v83
	v_lshl_add_u64 v[60:61], v[6:7], 0, v[68:69]
	v_and_b32_e32 v68, 0x70, v2
	v_readfirstlane_b32 s0, v1
	v_lshl_add_u64 v[2:3], v[60:61], 0, v[68:69]
	s_mov_b32 m0, s0
	v_lshrrev_b32_e32 v80, 4, v26
	global_load_lds_dwordx4 v[2:3], off
	v_or_b32_e32 v2, v81, v155
	v_mov_b32_e32 v3, v69
	v_lshlrev_b64 v[4:5], 8, v[2:3]
	v_add_u32_e32 v3, 0x4000, v1
	v_lshl_add_u64 v[62:63], v[10:11], 0, v[4:5]
	v_readfirstlane_b32 s0, v3
	v_or_b32_sdwa v3, v26, s34 dst_sel:DWORD dst_unused:UNUSED_PAD src0_sel:BYTE_0 src1_sel:DWORD
	v_lshl_add_u64 v[4:5], v[62:63], 0, v[68:69]
	s_mov_b32 m0, s0
	v_lshrrev_b32_e32 v156, 3, v3
	global_load_lds_dwordx4 v[4:5], off
	v_xor_b32_e32 v4, v156, v26
	v_lshlrev_b32_e32 v84, 4, v3
	v_lshlrev_b32_e32 v68, 8, v156
	v_lshlrev_b32_e32 v4, 4, v4
	v_add_u32_e32 v3, v102, v84
	v_lshl_add_u64 v[64:65], v[6:7], 0, v[68:69]
	v_and_b32_e32 v68, 0x70, v4
	v_readfirstlane_b32 s0, v3
	v_lshl_add_u64 v[4:5], v[64:65], 0, v[68:69]
	s_mov_b32 m0, s0
	v_and_b32_e32 v25, 7, v26
	global_load_lds_dwordx4 v[4:5], off
	v_or_b32_e32 v4, v81, v156
	v_mov_b32_e32 v5, v69
	v_lshlrev_b64 v[12:13], 8, v[4:5]
	v_add_u32_e32 v5, 0x4000, v3
	v_lshl_add_u64 v[76:77], v[10:11], 0, v[12:13]
	v_readfirstlane_b32 s0, v5
	v_or_b32_sdwa v5, v26, s35 dst_sel:DWORD dst_unused:UNUSED_PAD src0_sel:BYTE_0 src1_sel:DWORD
	v_lshl_add_u64 v[12:13], v[76:77], 0, v[68:69]
	s_mov_b32 m0, s0
	v_lshrrev_b32_e32 v157, 3, v5
	global_load_lds_dwordx4 v[12:13], off
	v_xor_b32_e32 v12, v157, v26
	v_lshlrev_b32_e32 v68, 8, v157
	v_lshlrev_b32_e32 v85, 4, v5
	v_lshl_add_u64 v[100:101], v[6:7], 0, v[68:69]
	v_lshlrev_b32_e32 v6, 4, v12
	v_add_u32_e32 v5, v102, v85
	v_and_b32_e32 v68, 0x70, v6
	v_readfirstlane_b32 s0, v5
	v_lshl_add_u64 v[6:7], v[100:101], 0, v[68:69]
	s_mov_b32 m0, s0
	v_and_b32_e32 v79, 15, v26
	global_load_lds_dwordx4 v[6:7], off
	v_or_b32_e32 v6, v81, v157
	v_mov_b32_e32 v7, v69
	v_lshlrev_b64 v[12:13], 8, v[6:7]
	v_add_u32_e32 v7, 0x4000, v5
	v_lshl_add_u64 v[148:149], v[10:11], 0, v[12:13]
	v_readfirstlane_b32 s0, v7
	v_lshl_add_u64 v[10:11], v[148:149], 0, v[68:69]
	s_mov_b32 m0, s0
	v_lshlrev_b32_e32 v68, 21, v70
	global_load_lds_dwordx4 v[10:11], off
	v_lshl_add_u64 v[10:11], s[6:7], 0, v[68:69]
	v_lshlrev_b32_e32 v68, 17, v71
	v_bfe_u32 v7, v26, 4, 2
	v_lshl_add_u64 v[152:153], v[10:11], 0, v[68:69]
	v_bitop3_b32 v10, v80, v25, 3 bitop3:0x6c
	v_bitop3_b32 v7, v7, v25, 4 bitop3:0x36
	v_bfe_u32 v78, v26, 6, 1
	v_bfe_u32 v86, v26, 7, 1
	v_lshlrev_b32_e32 v87, 4, v10
	v_lshlrev_b32_e32 v14, 7, v79
	v_lshlrev_b32_e32 v90, 4, v7
	v_lshlrev_b32_e32 v7, 7, v26
	v_lshl_or_b32 v88, v78, 13, v14
	v_add_u32_e32 v15, v102, v87
	v_lshl_or_b32 v89, v86, 13, v14
	v_lshlrev_b32_e32 v68, 10, v24
	v_and_b32_e32 v7, 0x3c00, v7
	v_bitop3_b32 v158, v24, 7, v26 bitop3:0x48
	v_add_u32_e32 v27, v15, v88
	v_add_u32_e32 v57, v15, v89
	v_lshl_add_u64 v[24:25], v[152:153], 0, v[68:69]
	v_lshl_or_b32 v68, v70, 14, v7
	s_waitcnt vmcnt(0)
	s_waitcnt vmcnt(0) lgkmcnt(0)
	s_barrier
; #define MFMA16(a, b, c) __builtin_amdgcn_mfma_f32_16x16x32_bf16((a), (b), (c), 0, 0, 0)
; #define LAS __attribute__((address_space(3)))
; template <class FA, class FB, class FL, class FS>
; DI void gemm_tile(char* lds, int ksteps, int rot, FA fa, FB fb, FL fl, FS fs) {
;     ...
;   for (int ks = 0; ks < ksteps; ++ks) {
;     const int cur = ks & 1;
;     if (ks + 1 < ksteps) {
;       int kn = ks + 1 + rot; if (kn >= ksteps) kn -= ksteps;
;       LAS char* dst = l3 + (cur ^ 1) * 32768;
; #pragma unroll
;       for (int i = 0; i < 4; ++i) {
;         const int id = tid + i * 256, r = id >> 3, c = (id & 7) ^ (r & 7);
;         __builtin_amdgcn_global_load_lds((const unsigned*)fa(r, kn * 8 + c), (LAS unsigned*)(dst + id * 16), 16, 0, 0);
;         __builtin_amdgcn_global_load_lds((const unsigned*)fb(r, kn * 8 + c), (LAS unsigned*)(dst + 16384 + id * 16), 16, 0, 0);
;       }
;     }
;     const char* A = lds + cur * 32768;
;     const char* B = A + 16384;
; #pragma unroll
;     for (int kk = 0; kk < 2; ++kk) {
;       bf16x8 af[4], bq[4];
; #pragma unroll
;       for (int m = 0; m < 4; ++m) af[m] = ldfrag(A, 128, wr * 64 + m * 16 + fr, kk * 4 + fq);
; #pragma unroll
;       for (int n = 0; n < 4; ++n) bq[n] = ldfrag(B, 128, wc * 64 + n * 16 + fr, kk * 4 + fq);
; #pragma unroll
;       for (int m = 0; m < 4; ++m)
; #pragma unroll
;         for (int n = 0; n < 4; ++n) acc[m][n] = MFMA16(bq[n], af[m], acc[m][n]);
	ds_read_b128 v[10:13], v27 offset:16384
	ds_read_b128 v[14:17], v57
	ds_read_b128 v[18:21], v27 offset:18432
	v_bitop3_b32 v159, v155, 7, v26 bitop3:0x48
	ds_read_b128 v[28:31], v57 offset:2048
	ds_read_b128 v[32:35], v27 offset:20480
	v_bitop3_b32 v160, v156, 7, v26 bitop3:0x48
	v_bitop3_b32 v161, v157, 7, v26 bitop3:0x48
	ds_read_b128 v[40:43], v27 offset:22528
	v_lshl_add_u64 v[26:27], s[12:13], 0, v[68:69]
	v_lshlrev_b32_e32 v68, 4, v158
	v_add_u32_e32 v7, 0x8000, v56
	v_lshl_add_u64 v[8:9], v[8:9], 0, v[68:69]
	v_readfirstlane_b32 s0, v7
	v_lshl_add_u64 v[8:9], v[8:9], 0, s[16:17]
	s_mov_b32 m0, s0
	v_add_u32_e32 v7, 0xc000, v56
	global_load_lds_dwordx4 v[8:9], off
	v_lshl_add_u64 v[8:9], v[22:23], 0, v[68:69]
	v_readfirstlane_b32 s0, v7
	v_add_u32_e32 v7, 0x8000, v1
	v_lshl_add_u64 v[8:9], v[8:9], 0, s[16:17]
	s_mov_b32 m0, s0
	v_readfirstlane_b32 s0, v7
	v_add_u32_e32 v1, 0xc000, v1
	global_load_lds_dwordx4 v[8:9], off
	s_mov_b32 m0, s0
	v_readfirstlane_b32 s0, v1
	v_add_u32_e32 v1, v102, v90
	v_lshlrev_b32_e32 v68, 4, v159
	v_add_u32_e32 v7, v1, v88
	s_waitcnt vmcnt(0)
	ds_read_b128 v[52:55], v57 offset:4096
	ds_read_b128 v[124:127], v7 offset:16384
	ds_read_b128 v[56:59], v57 offset:6144
	v_lshl_add_u64 v[8:9], v[60:61], 0, v[68:69]
	v_lshl_add_u64 v[8:9], v[8:9], 0, s[16:17]
	global_load_lds_dwordx4 v[8:9], off
	v_lshl_add_u64 v[8:9], v[62:63], 0, v[68:69]
	v_lshl_add_u64 v[22:23], v[8:9], 0, s[16:17]
	s_mov_b32 m0, s0
	v_add_u32_e32 v1, v1, v89
	global_load_lds_dwordx4 v[22:23], off
	s_waitcnt lgkmcnt(0)
	v_mfma_f32_16x16x32_bf16 v[44:47], v[18:21], v[14:17], 0
	v_lshlrev_b32_e32 v68, 4, v160
	v_add_u32_e32 v22, 0x8000, v3
	v_add_u32_e32 v3, 0xc000, v3
	v_mfma_f32_16x16x32_bf16 v[48:51], v[32:35], v[14:17], 0
	v_readfirstlane_b32 s0, v22
	s_mov_b32 m0, s0
	v_readfirstlane_b32 s0, v3
	v_mfma_f32_16x16x32_bf16 v[92:95], v[18:21], v[28:31], 0
	v_add_u32_e32 v3, 0x8000, v5
	v_lshl_add_u32 v91, v91, 1, 4
	s_mov_b32 s37, -9
	v_mfma_f32_16x16x32_bf16 v[96:99], v[32:35], v[28:31], 0
	s_mov_b32 s38, 0
	s_mov_b32 s39, 0x8000
	v_mfma_f32_16x16x32_bf16 v[108:111], v[18:21], v[52:55], 0
	v_mfma_f32_16x16x32_bf16 v[112:115], v[32:35], v[52:55], 0
	v_mfma_f32_16x16x32_bf16 v[120:123], v[18:21], v[56:59], 0
	s_waitcnt vmcnt(0)
	ds_read_b128 v[18:21], v1
	ds_read_b128 v[132:135], v7 offset:18432
	v_mfma_f32_16x16x32_bf16 v[128:131], v[32:35], v[56:59], 0
	ds_read_b128 v[32:35], v1 offset:2048
	ds_read_b128 v[140:143], v7 offset:20480
	ds_read_b128 v[144:147], v7 offset:22528
	v_mfma_f32_16x16x32_bf16 v[36:39], v[10:13], v[14:17], 0
	v_mfma_f32_16x16x32_bf16 v[72:75], v[10:13], v[28:31], 0
	v_mfma_f32_16x16x32_bf16 v[104:107], v[10:13], v[52:55], 0
	v_mfma_f32_16x16x32_bf16 v[8:11], v[10:13], v[56:59], 0
	v_lshl_add_u64 v[12:13], v[64:65], 0, v[68:69]
	v_lshl_add_u64 v[12:13], v[12:13], 0, s[16:17]
	global_load_lds_dwordx4 v[12:13], off
	v_lshl_add_u64 v[12:13], v[76:77], 0, v[68:69]
	v_mfma_f32_16x16x32_bf16 v[14:17], v[40:43], v[14:17], 0
	v_lshl_add_u64 v[12:13], v[12:13], 0, s[16:17]
	s_mov_b32 m0, s0
	v_lshlrev_b32_e32 v68, 4, v161
	global_load_lds_dwordx4 v[12:13], off
	v_lshl_add_u64 v[12:13], v[100:101], 0, v[68:69]
	v_readfirstlane_b32 s0, v3
	v_lshl_add_u64 v[12:13], v[12:13], 0, s[16:17]
	s_mov_b32 m0, s0
	v_add_u32_e32 v3, 0xc000, v5
	global_load_lds_dwordx4 v[12:13], off
	v_lshl_add_u64 v[12:13], v[148:149], 0, v[68:69]
	v_readfirstlane_b32 s0, v3
	v_mfma_f32_16x16x32_bf16 v[116:119], v[40:43], v[52:55], 0
	s_mov_b32 m0, s0
	s_waitcnt vmcnt(0)
	ds_read_b128 v[148:151], v1 offset:6144
	v_lshlrev_b32_e32 v76, 10, v157
	s_waitcnt lgkmcnt(0)
	v_mfma_f32_16x16x32_bf16 v[52:55], v[144:147], v[18:21], v[14:17]
	v_mov_b32_e32 v77, v69
	v_lshlrev_b32_e32 v68, 1, v154
	v_lshl_add_u64 v[76:77], v[152:153], 0, v[76:77]
	v_lshl_add_u64 v[16:17], v[12:13], 0, s[16:17]
	global_load_lds_dwordx4 v[16:17], off
	s_waitcnt vmcnt(0)
	ds_read_b128 v[12:15], v1 offset:4096
	v_mfma_f32_16x16x32_bf16 v[28:31], v[40:43], v[28:31], 0
	s_waitcnt vmcnt(0)
	v_sub_u32_e32 v100, 0, v68
	s_mov_b64 s[0:1], 0
	v_mfma_f32_16x16x32_bf16 v[136:139], v[40:43], v[56:59], 0
	s_waitcnt lgkmcnt(0)
	s_barrier
	v_mfma_f32_16x16x32_bf16 v[64:67], v[124:127], v[18:21], v[36:39]
	v_mfma_f32_16x16x32_bf16 v[60:63], v[132:135], v[18:21], v[44:47]
	v_mfma_f32_16x16x32_bf16 v[56:59], v[140:143], v[18:21], v[48:51]
	v_mfma_f32_16x16x32_bf16 v[48:51], v[124:127], v[32:35], v[72:75]
	v_mfma_f32_16x16x32_bf16 v[44:47], v[132:135], v[32:35], v[92:95]
	s_nop 1
	v_lshlrev_b32_e32 v72, 10, v155
	v_mov_b32_e32 v73, v69
	v_lshlrev_b32_e32 v74, 10, v156
	v_mfma_f32_16x16x32_bf16 v[40:43], v[140:143], v[32:35], v[96:99]
	v_lshrrev_b32_e32 v92, 4, v0
	v_lshrrev_b32_e32 v93, 4, v2
	v_lshrrev_b32_e32 v94, 4, v4
	v_mfma_f32_16x16x32_bf16 v[36:39], v[144:147], v[32:35], v[28:31]
	v_lshrrev_b32_e32 v95, 4, v6
	v_mov_b32_e32 v75, v69
	v_lshl_add_u64 v[72:73], v[152:153], 0, v[72:73]
	v_mfma_f32_16x16x32_bf16 v[32:35], v[124:127], v[12:15], v[104:107]
	v_lshl_add_u64 v[74:75], v[152:153], 0, v[74:75]
	v_lshlrev_b32_e32 v96, 3, v158
	v_lshlrev_b32_e32 v97, 3, v159
	v_mfma_f32_16x16x32_bf16 v[28:31], v[132:135], v[12:15], v[108:111]
	v_lshlrev_b32_e32 v98, 3, v160
	v_lshlrev_b32_e32 v99, 3, v161
	v_mfma_f32_16x16x32_bf16 v[20:23], v[140:143], v[12:15], v[112:115]
	v_mfma_f32_16x16x32_bf16 v[16:19], v[144:147], v[12:15], v[116:119]
	v_mfma_f32_16x16x32_bf16 v[12:15], v[124:127], v[148:151], v[8:11]
	v_mfma_f32_16x16x32_bf16 v[8:11], v[132:135], v[148:151], v[120:123]
	v_mfma_f32_16x16x32_bf16 v[4:7], v[140:143], v[148:151], v[128:131]
	v_mfma_f32_16x16x32_bf16 v[0:3], v[144:147], v[148:151], v[136:139]
	s_branch .LBB0_627

; DI float4 ldnt4(const float* p) { const f32x4 v = __builtin_nontemporal_load((const f32x4*)p); float4 r; r.x = v[0]; r.y = v[1]; r.z = v[2]; r.w = v[3]; return r; }
; DI void st_bf4(bf16_t* p, float a, float b, float c, float d) { uint2 v; v.x = pack2(a, b); v.y = pack2(c, d); *(uint2*)p = v; }
; DI void phase_gout(const Params& p, const Sub& s, char* lds_all, int layer, const bf16_t* A, const bf16_t* Bt) {
;   const float* mod = (const float*)(p.ws + W_MOD);
;   {
;     gemm_dispatch(s, lds_all, A, Bt, 4,
;       [&](int row, int col) {
;         const bf16_t* x1b = (const bf16_t*)p.out;
;         float4 x4;
;         if (layer == 0) x4 = ldnt4(xrow(p, row) + col);
;         else ld_bf4(x1b + (size_t)row * D + col, x4.x, x4.y, x4.z, x4.w);
;         Ld2 r; r.a = x4; r.b = *(const float4*)(mod + (size_t)(row_bi(row) * 2 + layer) * 3072 + 2048 + col);
;         return r;
;       },
;       [&](int row, int col, f32x4 v, const Ld2& l2) {
;         const float4 x4 = l2.a, g4 = l2.b;
;         bf16_t* x1b = (bf16_t*)p.out;
;         bf16_t* x2b = (bf16_t*)(p.ws + W_SLOT3);
;         st_bf4((layer == 0 ? x1b : x2b) + (size_t)row * D + col, x4.x + g4.x * v[0], x4.y + g4.y * v[1], x4.z + g4.z * v[2], x4.w + g4.w * v[3]);
;       });
.LBB0_744:
	s_or_b64 exec, exec, s[0:1]
	v_and_b32_e32 v140, 15, v182
	v_bfe_u32 v141, v182, 4, 2
	v_bfe_u32 v143, v182, 6, 2
	v_lshrrev_b32_e32 v180, 8, v182
	v_lshl_add_u32 v181, v180, 6, v140
	v_and_b32_e32 v248, 1, v141
	v_lshrrev_b32_e32 v249, 1, v141
	v_lshlrev_b32_e32 v250, 12, v181
	v_lshl_add_u32 v250, v143, 7, v250
	v_lshl_add_u32 v250, v141, 4, v250
	v_lshlrev_b32_e32 v232, 7, v143
	v_lshl_add_u32 v232, v141, 4, v232
	v_lshlrev_b32_e32 v233, 11, v181
	v_lshl_add_u32 v233, v143, 6, v233
	v_lshl_add_u32 v233, v248, 5, v233
	v_lshl_add_u32 v233, v249, 4, v233
	s_lshr_b32 s0, s44, 13
	s_mul_i32 s0, s0, 0x6000
	s_add_u32 s0, s0, 0x2000
	s_lshl_b32 s1, s42, 2
	s_add_u32 s0, s0, s1
	s_add_u32 s2, s6, s0
	s_addc_u32 s3, s7, 0
	s_lshl_b32 s0, s44, 12
	s_add_u32 s4, s12, s0
	s_addc_u32 s5, s13, 0
	s_lshl_b32 s0, s42, 2
	s_add_u32 s4, s4, s0
	s_addc_u32 s5, s5, 0
	s_lshl_b32 s0, s44, 11
	s_add_u32 s40, s8, s0
	s_addc_u32 s41, s9, 0
	s_lshl_b32 s0, s42, 1
	s_add_u32 s40, s40, s0
	s_addc_u32 s41, s41, 0
	global_load_dwordx4 v[128:131], v232, s[2:3]
	global_load_dwordx4 v[132:135], v232, s[2:3] offset:64
	global_load_dwordx4 v[136:139], v232, s[2:3] offset:512
	global_load_dwordx4 v[144:147], v232, s[2:3] offset:576
	global_load_dwordx4 v[148:151], v250, s[4:5] nt
	global_load_dwordx4 v[152:155], v250, s[4:5] offset:64 nt
	global_load_dwordx4 v[156:159], v250, s[4:5] offset:512 nt
	global_load_dwordx4 v[160:163], v250, s[4:5] offset:576 nt
	s_add_u32 s4, s4, 0x10000
	s_addc_u32 s5, s5, 0
	global_load_dwordx4 v[164:167], v250, s[4:5] nt
	global_load_dwordx4 v[168:171], v250, s[4:5] offset:64 nt
	global_load_dwordx4 v[172:175], v250, s[4:5] offset:512 nt
	global_load_dwordx4 v[176:179], v250, s[4:5] offset:576 nt
	s_add_u32 s4, s4, 0x10000
	s_addc_u32 s5, s5, 0
	global_load_dwordx4 v[184:187], v250, s[4:5] nt
	global_load_dwordx4 v[188:191], v250, s[4:5] offset:64 nt
	global_load_dwordx4 v[192:195], v250, s[4:5] offset:512 nt
	global_load_dwordx4 v[196:199], v250, s[4:5] offset:576 nt
	s_add_u32 s4, s4, 0x10000
	s_addc_u32 s5, s5, 0
	global_load_dwordx4 v[200:203], v250, s[4:5] nt
	global_load_dwordx4 v[204:207], v250, s[4:5] offset:64 nt
	global_load_dwordx4 v[208:211], v250, s[4:5] offset:512 nt
	global_load_dwordx4 v[212:215], v250, s[4:5] offset:576 nt
	s_add_u32 s4, s4, 0x50000
	s_addc_u32 s5, s5, 0
	global_load_dwordx4 v[216:219], v250, s[4:5] nt
	global_load_dwordx4 v[220:223], v250, s[4:5] offset:64 nt
	global_load_dwordx4 v[224:227], v250, s[4:5] offset:512 nt
	global_load_dwordx4 v[228:231], v250, s[4:5] offset:576 nt
	s_waitcnt vmcnt(16)
	v_pk_fma_f32 v[148:149], v[128:129], v[108:109], v[148:149]
	v_pk_fma_f32 v[150:151], v[130:131], v[110:111], v[150:151]
	v_pk_fma_f32 v[152:153], v[132:133], v[112:113], v[152:153]
	v_pk_fma_f32 v[154:155], v[134:135], v[114:115], v[154:155]
	v_pk_fma_f32 v[156:157], v[136:137], v[124:125], v[156:157]
	v_pk_fma_f32 v[158:159], v[138:139], v[126:127], v[158:159]
	v_pk_fma_f32 v[160:161], v[144:145], v[120:121], v[160:161]
	v_pk_fma_f32 v[162:163], v[146:147], v[122:123], v[162:163]
	v_cvt_pk_bf16_f32 v148, v148, v149
	v_cvt_pk_bf16_f32 v149, v150, v151
	v_cvt_pk_bf16_f32 v150, v152, v153
	v_cvt_pk_bf16_f32 v151, v154, v155
	v_cvt_pk_bf16_f32 v156, v156, v157
	v_cvt_pk_bf16_f32 v157, v158, v159
	v_cvt_pk_bf16_f32 v158, v160, v161
	v_cvt_pk_bf16_f32 v159, v162, v163
	v_permlane16_swap_b32_e32 v148, v150
	v_permlane16_swap_b32_e32 v149, v151
	global_store_dwordx4 v233, v[148:151], s[40:41]
	v_permlane16_swap_b32_e32 v156, v158
	v_permlane16_swap_b32_e32 v157, v159
	global_store_dwordx4 v233, v[156:159], s[40:41] offset:256
	s_nop 1
	s_add_u32 s4, s4, 0x10000
	s_addc_u32 s5, s5, 0
	global_load_dwordx4 v[148:151], v250, s[4:5] nt
	global_load_dwordx4 v[152:155], v250, s[4:5] offset:64 nt
	global_load_dwordx4 v[156:159], v250, s[4:5] offset:512 nt
	global_load_dwordx4 v[160:163], v250, s[4:5] offset:576 nt
	s_waitcnt vmcnt(18)
	v_pk_fma_f32 v[164:165], v[128:129], v[104:105], v[164:165]
	v_pk_fma_f32 v[166:167], v[130:131], v[106:107], v[166:167]
	v_pk_fma_f32 v[168:169], v[132:133], v[100:101], v[168:169]
	v_pk_fma_f32 v[170:171], v[134:135], v[102:103], v[170:171]
	v_pk_fma_f32 v[172:173], v[136:137], v[116:117], v[172:173]
	v_pk_fma_f32 v[174:175], v[138:139], v[118:119], v[174:175]
	v_pk_fma_f32 v[176:177], v[144:145], v[96:97], v[176:177]
	v_pk_fma_f32 v[178:179], v[146:147], v[98:99], v[178:179]
	v_cvt_pk_bf16_f32 v164, v164, v165
	v_cvt_pk_bf16_f32 v165, v166, v167
	v_cvt_pk_bf16_f32 v166, v168, v169
	v_cvt_pk_bf16_f32 v167, v170, v171
	v_cvt_pk_bf16_f32 v172, v172, v173
	v_cvt_pk_bf16_f32 v173, v174, v175
	v_cvt_pk_bf16_f32 v174, v176, v177
	v_cvt_pk_bf16_f32 v175, v178, v179
	s_add_u32 s40, s40, 0x8000
	s_addc_u32 s41, s41, 0
	v_permlane16_swap_b32_e32 v164, v166
	v_permlane16_swap_b32_e32 v165, v167
	global_store_dwordx4 v233, v[164:167], s[40:41]
	v_permlane16_swap_b32_e32 v172, v174
	v_permlane16_swap_b32_e32 v173, v175
	global_store_dwordx4 v233, v[172:175], s[40:41] offset:256
	s_nop 1
	s_add_u32 s4, s4, 0x10000
	s_addc_u32 s5, s5, 0
	global_load_dwordx4 v[164:167], v250, s[4:5] nt
	global_load_dwordx4 v[168:171], v250, s[4:5] offset:64 nt
	global_load_dwordx4 v[172:175], v250, s[4:5] offset:512 nt
	global_load_dwordx4 v[176:179], v250, s[4:5] offset:576 nt
	s_waitcnt vmcnt(20)
; DI float4 ldnt4(const float* p) { const f32x4 v = __builtin_nontemporal_load((const f32x4*)p); float4 r; r.x = v[0]; r.y = v[1]; r.z = v[2]; r.w = v[3]; return r; }
; DI void st_bf4(bf16_t* p, float a, float b, float c, float d) { uint2 v; v.x = pack2(a, b); v.y = pack2(c, d); *(uint2*)p = v; }
; DI void phase_gout(const Params& p, const Sub& s, char* lds_all, int layer, const bf16_t* A, const bf16_t* Bt) {
;     ...
;       [&](int row, int col) {
;         const bf16_t* x1b = (const bf16_t*)p.out;
;         float4 x4;
;         if (layer == 0) x4 = ldnt4(xrow(p, row) + col);
;         else ld_bf4(x1b + (size_t)row * D + col, x4.x, x4.y, x4.z, x4.w);
;         Ld2 r; r.a = x4; r.b = *(const float4*)(mod + (size_t)(row_bi(row) * 2 + layer) * 3072 + 2048 + col);
;         return r;
;       },
;       [&](int row, int col, f32x4 v, const Ld2& l2) {
;         const float4 x4 = l2.a, g4 = l2.b;
;         bf16_t* x1b = (bf16_t*)p.out;
;         bf16_t* x2b = (bf16_t*)(p.ws + W_SLOT3);
;         st_bf4((layer == 0 ? x1b : x2b) + (size_t)row * D + col, x4.x + g4.x * v[0], x4.y + g4.y * v[1], x4.z + g4.z * v[2], x4.w + g4.w * v[3]);
;       });
	v_pk_fma_f32 v[184:185], v[128:129], v[80:81], v[184:185]
	v_pk_fma_f32 v[186:187], v[130:131], v[82:83], v[186:187]
	v_pk_fma_f32 v[188:189], v[132:133], v[76:77], v[188:189]
	v_pk_fma_f32 v[190:191], v[134:135], v[78:79], v[190:191]
	v_pk_fma_f32 v[192:193], v[136:137], v[92:93], v[192:193]
	v_pk_fma_f32 v[194:195], v[138:139], v[94:95], v[194:195]
	v_pk_fma_f32 v[196:197], v[144:145], v[88:89], v[196:197]
	v_pk_fma_f32 v[198:199], v[146:147], v[90:91], v[198:199]
	v_cvt_pk_bf16_f32 v184, v184, v185
	v_cvt_pk_bf16_f32 v185, v186, v187
	v_cvt_pk_bf16_f32 v186, v188, v189
	v_cvt_pk_bf16_f32 v187, v190, v191
	v_cvt_pk_bf16_f32 v192, v192, v193
	v_cvt_pk_bf16_f32 v193, v194, v195
	v_cvt_pk_bf16_f32 v194, v196, v197
	v_cvt_pk_bf16_f32 v195, v198, v199
	s_add_u32 s40, s40, 0x8000
	s_addc_u32 s41, s41, 0
	v_permlane16_swap_b32_e32 v184, v186
	v_permlane16_swap_b32_e32 v185, v187
	global_store_dwordx4 v233, v[184:187], s[40:41]
	v_permlane16_swap_b32_e32 v192, v194
	v_permlane16_swap_b32_e32 v193, v195
	global_store_dwordx4 v233, v[192:195], s[40:41] offset:256
	s_nop 1
	s_add_u32 s4, s4, 0x10000
	s_addc_u32 s5, s5, 0
	global_load_dwordx4 v[184:187], v250, s[4:5] nt
	global_load_dwordx4 v[188:191], v250, s[4:5] offset:64 nt
	global_load_dwordx4 v[192:195], v250, s[4:5] offset:512 nt
	global_load_dwordx4 v[196:199], v250, s[4:5] offset:576 nt
	s_waitcnt vmcnt(22)
	v_pk_fma_f32 v[200:201], v[128:129], v[72:73], v[200:201]
	v_pk_fma_f32 v[202:203], v[130:131], v[74:75], v[202:203]
	v_pk_fma_f32 v[204:205], v[132:133], v[68:69], v[204:205]
	v_pk_fma_f32 v[206:207], v[134:135], v[70:71], v[206:207]
	v_pk_fma_f32 v[208:209], v[136:137], v[84:85], v[208:209]
	v_pk_fma_f32 v[210:211], v[138:139], v[86:87], v[210:211]
	v_pk_fma_f32 v[212:213], v[144:145], v[64:65], v[212:213]
	v_pk_fma_f32 v[214:215], v[146:147], v[66:67], v[214:215]
	v_cvt_pk_bf16_f32 v200, v200, v201
	v_cvt_pk_bf16_f32 v201, v202, v203
	v_cvt_pk_bf16_f32 v202, v204, v205
	v_cvt_pk_bf16_f32 v203, v206, v207
	v_cvt_pk_bf16_f32 v208, v208, v209
	v_cvt_pk_bf16_f32 v209, v210, v211
	v_cvt_pk_bf16_f32 v210, v212, v213
	v_cvt_pk_bf16_f32 v211, v214, v215
	s_add_u32 s40, s40, 0x8000
	s_addc_u32 s41, s41, 0
	v_permlane16_swap_b32_e32 v200, v202
	v_permlane16_swap_b32_e32 v201, v203
	global_store_dwordx4 v233, v[200:203], s[40:41]
	v_permlane16_swap_b32_e32 v208, v210
	v_permlane16_swap_b32_e32 v209, v211
	global_store_dwordx4 v233, v[208:211], s[40:41] offset:256
	s_waitcnt vmcnt(20)
	v_pk_fma_f32 v[216:217], v[128:129], v[52:53], v[216:217]
	v_pk_fma_f32 v[218:219], v[130:131], v[54:55], v[218:219]
	v_pk_fma_f32 v[220:221], v[132:133], v[48:49], v[220:221]
	v_pk_fma_f32 v[222:223], v[134:135], v[50:51], v[222:223]
	v_pk_fma_f32 v[224:225], v[136:137], v[60:61], v[224:225]
	v_pk_fma_f32 v[226:227], v[138:139], v[62:63], v[226:227]
	v_pk_fma_f32 v[228:229], v[144:145], v[56:57], v[228:229]
	v_pk_fma_f32 v[230:231], v[146:147], v[58:59], v[230:231]
	v_cvt_pk_bf16_f32 v216, v216, v217
	v_cvt_pk_bf16_f32 v217, v218, v219
	v_cvt_pk_bf16_f32 v218, v220, v221
	v_cvt_pk_bf16_f32 v219, v222, v223
	v_cvt_pk_bf16_f32 v224, v224, v225
	v_cvt_pk_bf16_f32 v225, v226, v227
	v_cvt_pk_bf16_f32 v226, v228, v229
	v_cvt_pk_bf16_f32 v227, v230, v231
	s_add_u32 s40, s40, 0x28000
	s_addc_u32 s41, s41, 0
	v_permlane16_swap_b32_e32 v216, v218
	v_permlane16_swap_b32_e32 v217, v219
	global_store_dwordx4 v233, v[216:219], s[40:41]
	v_permlane16_swap_b32_e32 v224, v226
	v_permlane16_swap_b32_e32 v225, v227
	global_store_dwordx4 v233, v[224:227], s[40:41] offset:256
	s_waitcnt vmcnt(16)
	v_pk_fma_f32 v[148:149], v[128:129], v[40:41], v[148:149]
	v_pk_fma_f32 v[150:151], v[130:131], v[42:43], v[150:151]
	v_pk_fma_f32 v[152:153], v[132:133], v[36:37], v[152:153]
	v_pk_fma_f32 v[154:155], v[134:135], v[38:39], v[154:155]
	v_pk_fma_f32 v[156:157], v[136:137], v[44:45], v[156:157]
	v_pk_fma_f32 v[158:159], v[138:139], v[46:47], v[158:159]
	v_pk_fma_f32 v[160:161], v[144:145], v[32:33], v[160:161]
	v_pk_fma_f32 v[162:163], v[146:147], v[34:35], v[162:163]
	v_cvt_pk_bf16_f32 v148, v148, v149
	v_cvt_pk_bf16_f32 v149, v150, v151
	v_cvt_pk_bf16_f32 v150, v152, v153
	v_cvt_pk_bf16_f32 v151, v154, v155
	v_cvt_pk_bf16_f32 v156, v156, v157
	v_cvt_pk_bf16_f32 v157, v158, v159
	v_cvt_pk_bf16_f32 v158, v160, v161
	v_cvt_pk_bf16_f32 v159, v162, v163
	s_add_u32 s40, s40, 0x8000
	s_addc_u32 s41, s41, 0
	v_permlane16_swap_b32_e32 v148, v150
	v_permlane16_swap_b32_e32 v149, v151
	global_store_dwordx4 v233, v[148:151], s[40:41]
	v_permlane16_swap_b32_e32 v156, v158
	v_permlane16_swap_b32_e32 v157, v159
	global_store_dwordx4 v233, v[156:159], s[40:41] offset:256
	s_waitcnt vmcnt(12)
	v_pk_fma_f32 v[164:165], v[128:129], v[20:21], v[164:165]
	v_pk_fma_f32 v[166:167], v[130:131], v[22:23], v[166:167]
	v_pk_fma_f32 v[168:169], v[132:133], v[16:17], v[168:169]
	v_pk_fma_f32 v[170:171], v[134:135], v[18:19], v[170:171]
	v_pk_fma_f32 v[172:173], v[136:137], v[28:29], v[172:173]
	v_pk_fma_f32 v[174:175], v[138:139], v[30:31], v[174:175]
	v_pk_fma_f32 v[176:177], v[144:145], v[24:25], v[176:177]
	v_pk_fma_f32 v[178:179], v[146:147], v[26:27], v[178:179]
	v_cvt_pk_bf16_f32 v164, v164, v165
	v_cvt_pk_bf16_f32 v165, v166, v167
	v_cvt_pk_bf16_f32 v166, v168, v169
	v_cvt_pk_bf16_f32 v167, v170, v171
	v_cvt_pk_bf16_f32 v172, v172, v173
	v_cvt_pk_bf16_f32 v173, v174, v175
	v_cvt_pk_bf16_f32 v174, v176, v177
	v_cvt_pk_bf16_f32 v175, v178, v179
	s_add_u32 s40, s40, 0x8000
	s_addc_u32 s41, s41, 0
	v_permlane16_swap_b32_e32 v164, v166
	v_permlane16_swap_b32_e32 v165, v167
	global_store_dwordx4 v233, v[164:167], s[40:41]
	v_permlane16_swap_b32_e32 v172, v174
	v_permlane16_swap_b32_e32 v173, v175
	global_store_dwordx4 v233, v[172:175], s[40:41] offset:256
	s_waitcnt vmcnt(8)
	v_pk_fma_f32 v[184:185], v[128:129], v[8:9], v[184:185]
	v_pk_fma_f32 v[186:187], v[130:131], v[10:11], v[186:187]
	v_pk_fma_f32 v[188:189], v[132:133], v[4:5], v[188:189]
	v_pk_fma_f32 v[190:191], v[134:135], v[6:7], v[190:191]
	v_pk_fma_f32 v[192:193], v[136:137], v[12:13], v[192:193]
	v_pk_fma_f32 v[194:195], v[138:139], v[14:15], v[194:195]
	v_pk_fma_f32 v[196:197], v[144:145], v[0:1], v[196:197]
	v_pk_fma_f32 v[198:199], v[146:147], v[2:3], v[198:199]
	v_cvt_pk_bf16_f32 v184, v184, v185
	v_cvt_pk_bf16_f32 v185, v186, v187
	v_cvt_pk_bf16_f32 v186, v188, v189
	v_cvt_pk_bf16_f32 v187, v190, v191
	v_cvt_pk_bf16_f32 v192, v192, v193
	v_cvt_pk_bf16_f32 v193, v194, v195
	v_cvt_pk_bf16_f32 v194, v196, v197
	v_cvt_pk_bf16_f32 v195, v198, v199
	s_add_u32 s40, s40, 0x8000
	s_addc_u32 s41, s41, 0
	v_permlane16_swap_b32_e32 v184, v186
	v_permlane16_swap_b32_e32 v185, v187
	global_store_dwordx4 v233, v[184:187], s[40:41]
	v_permlane16_swap_b32_e32 v192, v194
	v_permlane16_swap_b32_e32 v193, v195
	global_store_dwordx4 v233, v[192:195], s[40:41] offset:256
	v_readlane_b32 s0, v251, 1
	s_add_i32 s56, s56, s0
	s_cmpk_lt_i32 s56, 0x400
	s_waitcnt vmcnt(0)
	s_barrier
	s_cbranch_scc0 .LBB0_751

; DI int otid() { int t = threadIdx.x; asm volatile("" : "+v"(t)); return t; }
; #define LAS __attribute__((address_space(3)))
; #define DMA_GT(cid_, slot_) do { if (wave == 0) __builtin_amdgcn_global_load_lds((const unsigned*)(GGC + ((size_t)(cid_) * 8 + hv) * 256 + lane * 4), \
;       (LAS unsigned*)((LAS char*)lds_all + 131072 + (slot_) * 1024 + lane * 16), 16, 0, 0); } while (0)
; DI void phase_gdn_seq(const Params& p, const Sub& s, char* lds_all) {
;     ...
;   for (int rb = blockIdx.x; rb < 256; rb += gridDim.x) {
;     if ((rb >= 128) != s.samp) continue;
;     const int hh = otid() >> 8;
;     const bool act = rb >= 128 || hh == 0;
;     const int it = rb < 128 ? rb : 128 + (rb - 128) * 2 + hh;
;     const bool samp = it >= 128;
;     int b, hv, half, nsteps, cid0;
;     if (!samp) { b = it >> 4; hv = (it >> 1) & 7; half = it & 1; nsteps = 128; cid0 = b * 128; }
;     else { const int s = it - 128; b = s >> 4; hv = (s >> 1) & 7; half = s & 1; nsteps = 1; cid0 = 1024 + b; }
;     const int hq = hv >> 1, dv0 = half * 64 + wave * 16;
;     const int tv = samp ? 16 : 64;
;     f32x4 S[8];
; #pragma unroll
;     for (int m = 0; m < 8; ++m) {
;       S[m] = (f32x4){0.f, 0.f, 0.f, 0.f};
;       if (samp && act) {
; #pragma unroll
;         for (int j = 0; j < 4; ++j) S[m][j] = p.st_gdn[(((size_t)b * 8 + hv) * 128 + m * 16 + 4 * fq + j) * 128 + dv0 + fr];
;       }
;     }
;     ...
;     char* lbase = rb < 128 ? lds_all : lds_all + ((otid() >> 8) << 16);
;     LAS char* l3 = (LAS char*)lbase;
;     ...
;     const bool ldr = rb < 128 ? (hh == 1) : true;
;     if (ldr) { DMA_WU(cid0, 0); DMA_QK(cid0, 0); DMA_GT(cid0, rb < 128 ? 0 : hh); }
.LBB0_1959:
	s_cmpk_gt_i32 s62, 0x7f
	s_cbranch_scc1 .LBB0_1958
	s_and_b32 s98, s62, 7
	s_lshl_b32 s98, s98, 4
	s_lshr_b32 s99, s62, 3
	s_or_b32 s98, s98, s99
	s_ashr_i32 s38, s98, 4
	v_mov_b32_e32 v0, v182
	s_lshl_b32 s0, s38, 7
	s_lshr_b32 s1, s98, 1
	v_and_b32_e32 v2, 0xffffff00, v0
	s_bfe_u32 s12, s98, 0x30001
	s_and_b32 s39, s98, 1
	s_bfe_u32 s40, s1, 0x20001
	v_cmp_eq_u32_e64 s[6:7], s53, v2
	v_cmp_ne_u32_e32 vcc, s53, v2
	s_and_saveexec_b64 s[2:3], vcc
	s_xor_b64 s[2:3], exec, s[2:3]
	s_lshl_b32 s4, s39, 12
	s_mov_b32 s5, s13
	s_lshl_b32 s8, s40, 13
	s_mov_b32 s9, s13
	s_ashr_i32 s1, s0, 31
	s_or_saveexec_b64 s[2:3], s[2:3]
	v_mov_b64_e32 v[2:3], s[0:1]
	v_mov_b64_e32 v[6:7], s[8:9]
	v_mov_b64_e32 v[4:5], s[4:5]
	v_mov_b64_e32 v[8:9], s[12:13]
	s_xor_b64 exec, exec, s[2:3]
	s_cbranch_execz .LBB0_1966
	s_ashr_i32 s1, s0, 31
	s_lshl_b64 s[4:5], s[0:1], 3
	s_or_b32 s4, s4, s12
	s_lshl_b64 s[8:9], s[4:5], 13
	s_lshl_b64 s[64:65], s[4:5], 14
	s_add_u32 s66, s33, s64
	s_addc_u32 s67, s42, s65
	v_mov_b32_e32 v73, v1
	v_lshl_add_u64 v[2:3], s[66:67], 0, v[72:73]
	v_mov_b32_e32 v75, v1
	v_readfirstlane_b32 s41, v106
	v_lshl_add_u64 v[2:3], v[2:3], 0, v[74:75]
	s_mov_b32 m0, s41
	v_mov_b32_e32 v77, v1
	global_load_lds_dwordx4 v[2:3], off
	v_lshl_add_u64 v[2:3], s[66:67], 0, v[76:77]
	v_readfirstlane_b32 s41, v107
	v_lshl_add_u64 v[2:3], v[2:3], 0, v[74:75]
	s_mov_b32 m0, s41
	v_mov_b32_e32 v79, v1
	global_load_lds_dwordx4 v[2:3], off
	v_lshl_add_u64 v[2:3], s[66:67], 0, v[78:79]
	v_readfirstlane_b32 s41, v108
	v_lshl_add_u64 v[2:3], v[2:3], 0, v[74:75]
	s_mov_b32 m0, s41
	v_readfirstlane_b32 s41, v109
	global_load_lds_dwordx4 v[2:3], off
	v_mov_b32_e32 v81, v1
	s_mov_b32 m0, s41
	s_add_u32 s41, s43, s64
	v_lshl_add_u64 v[2:3], s[66:67], 0, v[80:81]
	s_addc_u32 s63, s44, s65
	s_lshl_b32 s64, s39, 13
	v_lshl_add_u64 v[2:3], v[2:3], 0, v[74:75]
	s_add_u32 s64, s41, s64
	v_readfirstlane_b32 s41, v112
	global_load_lds_dwordx4 v[2:3], off
	s_addc_u32 s65, s63, 0
	s_mov_b32 m0, s41
	v_readfirstlane_b32 s41, v114
	global_load_lds_dwordx4 v111, s[64:65]
	s_mov_b32 m0, s41
	s_lshl_b32 s41, s40, 14
	global_load_lds_dwordx4 v113, s[64:65]
	s_lshl_b64 s[64:65], s[0:1], 16
	s_or_b32 s41, s64, s41
	s_add_u32 s66, s47, s41
	s_addc_u32 s67, s48, s65
	s_add_u32 s64, s49, s41
	v_lshl_add_u64 v[2:3], s[66:67], 0, v[72:73]
	v_readfirstlane_b32 s41, v115
	v_lshl_add_u64 v[2:3], v[2:3], 0, v[74:75]
	s_mov_b32 m0, s41
	v_readfirstlane_b32 s41, v116
	global_load_lds_dwordx4 v[2:3], off
	v_lshl_add_u64 v[2:3], s[66:67], 0, v[76:77]
	v_lshl_add_u64 v[2:3], v[2:3], 0, v[74:75]
	s_mov_b32 m0, s41
	v_readfirstlane_b32 s41, v117
	global_load_lds_dwordx4 v[2:3], off
	v_lshl_add_u64 v[2:3], s[66:67], 0, v[78:79]
	v_lshl_add_u64 v[2:3], v[2:3], 0, v[74:75]
	s_mov_b32 m0, s41
	v_readfirstlane_b32 s41, v118
	global_load_lds_dwordx4 v[2:3], off
	v_lshl_add_u64 v[2:3], s[66:67], 0, v[80:81]
	s_addc_u32 s65, s50, s65
	v_lshl_add_u64 v[2:3], v[2:3], 0, v[74:75]
	s_mov_b32 m0, s41
	v_mov_b32_e32 v83, v1
	global_load_lds_dwordx4 v[2:3], off
	v_lshl_add_u64 v[2:3], s[64:65], 0, v[82:83]
	v_mov_b32_e32 v85, v1
	v_readfirstlane_b32 s41, v119
	v_lshl_add_u64 v[2:3], v[2:3], 0, v[84:85]
	s_mov_b32 m0, s41
	v_mov_b32_e32 v87, v1
	global_load_lds_dwordx4 v[2:3], off
	v_lshl_add_u64 v[2:3], s[64:65], 0, v[86:87]
	v_mov_b32_e32 v89, v1
	v_readfirstlane_b32 s41, v120
	v_lshl_add_u64 v[2:3], v[2:3], 0, v[88:89]
	s_mov_b32 m0, s41
	v_mov_b32_e32 v91, v1
	global_load_lds_dwordx4 v[2:3], off
	v_lshl_add_u64 v[2:3], s[64:65], 0, v[90:91]
	v_mov_b32_e32 v93, v1
	v_readfirstlane_b32 s41, v121
	v_lshl_add_u64 v[2:3], v[2:3], 0, v[92:93]
	s_mov_b32 m0, s41
	v_mov_b32_e32 v95, v1
	global_load_lds_dwordx4 v[2:3], off
	v_lshl_add_u64 v[2:3], s[64:65], 0, v[94:95]
	v_mov_b32_e32 v97, v1
	v_readfirstlane_b32 s41, v122
	s_add_u32 s8, s45, s8
	v_lshl_add_u64 v[2:3], v[2:3], 0, v[96:97]
	s_mov_b32 m0, s41
	s_addc_u32 s9, s46, s9
	global_load_lds_dwordx4 v[2:3], off
	v_lshl_add_u64 v[2:3], s[8:9], 0, v[82:83]
	v_readfirstlane_b32 s41, v123
	v_lshl_add_u64 v[2:3], v[2:3], 0, v[84:85]
	s_mov_b32 m0, s41
	s_nop 0
	global_load_lds_dwordx4 v[2:3], off
	v_lshl_add_u64 v[2:3], s[8:9], 0, v[86:87]
	v_readfirstlane_b32 s8, v124
	v_lshl_add_u64 v[2:3], v[2:3], 0, v[88:89]
	s_mov_b32 m0, s8
	s_nop 0
	global_load_lds_dwordx4 v[2:3], off
	s_and_saveexec_b64 s[8:9], s[14:15]
	s_cbranch_execz .LBB0_1965
	s_lshl_b64 s[4:5], s[4:5], 10
	v_lshl_add_u64 v[2:3], v[70:71], 0, s[4:5]
	v_readfirstlane_b32 s4, v125
	s_mov_b32 m0, s4
	s_nop 0
	global_load_lds_dwordx4 v[2:3], off

; __global__ void __launch_bounds__(512, 1) fwd_megakernel(Params p) {
;   __shared__ __attribute__((aligned(16))) char lds_all[LDS_BYTES];
	.amdhsa_kernel _Z14fwd_megakernel6Params
		.amdhsa_group_segment_fixed_size 133136
		.amdhsa_private_segment_fixed_size 0
		.amdhsa_kernarg_size 512
		.amdhsa_user_sgpr_count 2
		.amdhsa_user_sgpr_dispatch_ptr 0
		.amdhsa_user_sgpr_queue_ptr 0
		.amdhsa_user_sgpr_kernarg_segment_ptr 1
		.amdhsa_user_sgpr_dispatch_id 0
		.amdhsa_user_sgpr_kernarg_preload_length 0
		.amdhsa_user_sgpr_kernarg_preload_offset 0
		.amdhsa_user_sgpr_private_segment_size 0
		.amdhsa_uses_dynamic_stack 0
		.amdhsa_enable_private_segment 0
		.amdhsa_system_sgpr_workgroup_id_x 1
		.amdhsa_system_sgpr_workgroup_id_y 0
		.amdhsa_system_sgpr_workgroup_id_z 0
		.amdhsa_system_sgpr_workgroup_info 0
		.amdhsa_system_vgpr_workitem_id 2
		.amdhsa_next_free_vgpr 252
		.amdhsa_next_free_sgpr 102
		.amdhsa_accum_offset 252
		.amdhsa_reserve_vcc 1
		.amdhsa_float_round_mode_32 0
		.amdhsa_float_round_mode_16_64 0
		.amdhsa_float_denorm_mode_32 3
		.amdhsa_float_denorm_mode_16_64 3
		.amdhsa_dx10_clamp 1
		.amdhsa_ieee_mode 1
		.amdhsa_fp16_overflow 0
		.amdhsa_tg_split 0
		.amdhsa_exception_fp_ieee_invalid_op 0
		.amdhsa_exception_fp_denorm_src 0
		.amdhsa_exception_fp_ieee_div_zero 0
		.amdhsa_exception_fp_ieee_overflow 0
		.amdhsa_exception_fp_ieee_underflow 0
		.amdhsa_exception_fp_ieee_inexact 0
		.amdhsa_exception_int_div_zero 0
	.end_amdhsa_kernel

; __global__ void __launch_bounds__(512, 1) fwd_megakernel(Params p) {
;   __shared__ __attribute__((aligned(16))) char lds_all[LDS_BYTES];
amdhsa.kernels:
  - .agpr_count:     0
    .args:
      - .offset:         0
        .size:           256
        .value_kind:     by_value
      - .offset:         256
        .size:           4
        .value_kind:     hidden_block_count_x
      - .offset:         260
        .size:           4
        .value_kind:     hidden_block_count_y
      - .offset:         264
        .size:           4
        .value_kind:     hidden_block_count_z
      - .offset:         268
        .size:           2
        .value_kind:     hidden_group_size_x
      - .offset:         270
        .size:           2
        .value_kind:     hidden_group_size_y
      - .offset:         272
        .size:           2
        .value_kind:     hidden_group_size_z
      - .offset:         274
        .size:           2
        .value_kind:     hidden_remainder_x
      - .offset:         276
        .size:           2
        .value_kind:     hidden_remainder_y
      - .offset:         278
        .size:           2
        .value_kind:     hidden_remainder_z
      - .offset:         296
        .size:           8
        .value_kind:     hidden_global_offset_x
      - .offset:         304
        .size:           8
        .value_kind:     hidden_global_offset_y
      - .offset:         312
        .size:           8
        .value_kind:     hidden_global_offset_z
      - .offset:         320
        .size:           2
        .value_kind:     hidden_grid_dims
      - .offset:         344
        .size:           8
        .value_kind:     hidden_multigrid_sync_arg
    .group_segment_fixed_size: 133136
    .kernarg_segment_align: 8
    .kernarg_segment_size: 512
    .language:       OpenCL C
    .language_version:
      - 2
      - 0
    .max_flat_workgroup_size: 512
    .name:           _Z14fwd_megakernel6Params
    .private_segment_fixed_size: 0
    .sgpr_count:     108
    .sgpr_spill_count: 266
    .symbol:         _Z14fwd_megakernel6Params.kd
    .uniform_work_group_size: 1
    .uses_dynamic_stack: false
    .vgpr_count:     252
    .vgpr_spill_count: 0
    .wavefront_size: 64
